# v12 + LDS-DMA issue hoisted before the ds_reads in all 20 GEMM K-loop load segments
# baseline (speedup 1.0000x reference)
.LBB0_252:
	s_add_u32 s12, s54, 0xfff00080
	s_addc_u32 s13, s55, -1
	s_add_i32 s95, 0, 0x10000
	s_cmp_eq_u32 s94, 60
	s_cselect_b32 s65, s47, s13
	s_cselect_b32 s64, s66, s12
	s_cselect_b32 s63, s45, s61
	s_cselect_b32 s62, vcc_lo, vcc_hi
	s_add_i32 s56, 0, 0x14000
	v_lshl_add_u64 v[142:143], s[54:55], 0, v[136:137]
	s_add_i32 m0, s53, 0xc000
	global_load_lds_dwordx4 v[142:143], off
	v_lshl_add_u64 v[142:143], s[54:55], 0, v[138:139]
	s_add_i32 m0, s53, 0xe000
	s_nop 0
	global_load_lds_dwordx4 v[142:143], off
	v_add_u32_e32 v142, s95, v144
	ds_read_b128 v[148:151], v142
	ds_read_b128 v[152:155], v142 offset:1024
	ds_read_b128 v[156:159], v142 offset:2048
	ds_read_b128 v[160:163], v142 offset:3072
	v_add_u32_e32 v142, s56, v144
	ds_read_b128 v[164:167], v142
	ds_read_b128 v[168:171], v142 offset:1024
	ds_read_b128 v[172:175], v142 offset:2048
	ds_read_b128 v[176:179], v142 offset:3072
	ds_read_b128 v[180:183], v146
	ds_read_b128 v[184:187], v146 offset:1024
	ds_read_b128 v[210:213], v146 offset:2048
	ds_read_b128 v[214:217], v146 offset:3072
	ds_read_b128 v[218:221], v146 offset:4096
	ds_read_b128 v[222:225], v146 offset:5120
	ds_read_b128 v[226:229], v146 offset:6144
	ds_read_b128 v[230:233], v146 offset:7168
	s_waitcnt vmcnt(8)
	s_waitcnt lgkmcnt(0)
	s_barrier
	s_setprio 1
	s_waitcnt lgkmcnt(0)
	v_mfma_f32_16x16x32_bf16 v[126:129], v[148:151], v[180:183], v[126:129]
	v_mfma_f32_16x16x32_bf16 v[126:129], v[152:155], v[184:187], v[126:129]
	v_mfma_f32_16x16x32_bf16 v[114:117], v[152:155], v[214:217], v[114:117]
	v_mfma_f32_16x16x32_bf16 v[114:117], v[148:151], v[210:213], v[114:117]
	v_mfma_f32_16x16x32_bf16 v[98:101], v[148:151], v[218:221], v[98:101]
	v_mfma_f32_16x16x32_bf16 v[98:101], v[152:155], v[222:225], v[98:101]
	v_mfma_f32_16x16x32_bf16 v[82:85], v[152:155], v[230:233], v[82:85]
	v_mfma_f32_16x16x32_bf16 v[82:85], v[148:151], v[226:229], v[82:85]
	v_mfma_f32_16x16x32_bf16 v[74:77], v[156:159], v[226:229], v[74:77]
	v_mfma_f32_16x16x32_bf16 v[74:77], v[160:163], v[230:233], v[74:77]
	v_mfma_f32_16x16x32_bf16 v[90:93], v[160:163], v[222:225], v[90:93]
	v_mfma_f32_16x16x32_bf16 v[90:93], v[156:159], v[218:221], v[90:93]
	v_mfma_f32_16x16x32_bf16 v[106:109], v[156:159], v[210:213], v[106:109]
	v_mfma_f32_16x16x32_bf16 v[106:109], v[160:163], v[214:217], v[106:109]
	v_mfma_f32_16x16x32_bf16 v[122:125], v[160:163], v[184:187], v[122:125]
	v_mfma_f32_16x16x32_bf16 v[122:125], v[156:159], v[180:183], v[122:125]
	v_mfma_f32_16x16x32_bf16 v[110:113], v[172:175], v[180:183], v[110:113]
	v_mfma_f32_16x16x32_bf16 v[110:113], v[176:179], v[184:187], v[110:113]
	v_mfma_f32_16x16x32_bf16 v[94:97], v[176:179], v[214:217], v[94:97]
	v_mfma_f32_16x16x32_bf16 v[94:97], v[172:175], v[210:213], v[94:97]
	v_mfma_f32_16x16x32_bf16 v[78:81], v[172:175], v[218:221], v[78:81]
	v_mfma_f32_16x16x32_bf16 v[78:81], v[176:179], v[222:225], v[78:81]
	v_mfma_f32_16x16x32_bf16 v[66:69], v[176:179], v[230:233], v[66:69]
	v_mfma_f32_16x16x32_bf16 v[66:69], v[172:175], v[226:229], v[66:69]
	v_mfma_f32_16x16x32_bf16 v[70:73], v[164:167], v[226:229], v[70:73]
	v_mfma_f32_16x16x32_bf16 v[70:73], v[168:171], v[230:233], v[70:73]
	v_mfma_f32_16x16x32_bf16 v[86:89], v[168:171], v[222:225], v[86:89]
	v_mfma_f32_16x16x32_bf16 v[86:89], v[164:167], v[218:221], v[86:89]
	v_mfma_f32_16x16x32_bf16 v[102:105], v[164:167], v[210:213], v[102:105]
	v_mfma_f32_16x16x32_bf16 v[102:105], v[168:171], v[214:217], v[102:105]
	v_mfma_f32_16x16x32_bf16 v[118:121], v[168:171], v[184:187], v[118:121]
	v_mfma_f32_16x16x32_bf16 v[118:121], v[164:167], v[180:183], v[118:121]
	s_setprio 0
	s_barrier
	s_add_i32 s12, s95, s82
	v_lshl_add_u64 v[142:143], s[62:63], 0, v[190:191]
	s_mov_b32 m0, s12
	global_load_lds_dwordx4 v[142:143], off
	s_add_i32 m0, s12, 0x2000
	s_add_u32 s12, s62, 0x100000
	v_lshl_add_u64 v[188:189], s[62:63], 0, v[134:135]
	s_addc_u32 s13, s63, 0
	s_add_i32 s56, s56, s82
	global_load_lds_dwordx4 v[188:189], off
	v_lshl_add_u64 v[234:235], s[12:13], 0, v[190:191]
	s_mov_b32 m0, s56
	v_lshl_add_u64 v[244:245], s[64:65], 0, v[132:133]
	global_load_lds_dwordx4 v[234:235], off
	v_lshl_add_u64 v[234:235], s[12:13], 0, v[134:135]
	s_add_i32 m0, s56, 0x2000
	s_nop 0
	global_load_lds_dwordx4 v[234:235], off
	v_lshl_add_u64 v[234:235], s[64:65], 0, v[130:131]
	s_mov_b32 m0, s53
	s_nop 0
	global_load_lds_dwordx4 v[234:235], off
	s_mov_b32 m0, s84
	s_nop 0
	global_load_lds_dwordx4 v[244:245], off
	ds_read_b128 v[180:183], v146 offset:16384
	ds_read_b128 v[184:187], v146 offset:17408
	ds_read_b128 v[210:213], v146 offset:18432
	ds_read_b128 v[214:217], v146 offset:19456
	ds_read_b128 v[218:221], v146 offset:20480
	ds_read_b128 v[222:225], v146 offset:21504
	ds_read_b128 v[226:229], v146 offset:22528
	ds_read_b128 v[230:233], v146 offset:23552
	s_waitcnt vmcnt(8)
	s_waitcnt lgkmcnt(0)
	s_barrier
	s_setprio 1
	s_waitcnt lgkmcnt(0)
	v_mfma_f32_16x16x32_bf16 v[62:65], v[148:151], v[180:183], v[62:65]
	v_mfma_f32_16x16x32_bf16 v[62:65], v[152:155], v[184:187], v[62:65]
	v_mfma_f32_16x16x32_bf16 v[50:53], v[152:155], v[214:217], v[50:53]
	v_mfma_f32_16x16x32_bf16 v[50:53], v[148:151], v[210:213], v[50:53]
	v_mfma_f32_16x16x32_bf16 v[34:37], v[148:151], v[218:221], v[34:37]
	v_mfma_f32_16x16x32_bf16 v[34:37], v[152:155], v[222:225], v[34:37]
	v_mfma_f32_16x16x32_bf16 v[18:21], v[152:155], v[230:233], v[18:21]
	v_mfma_f32_16x16x32_bf16 v[18:21], v[148:151], v[226:229], v[18:21]
	v_mfma_f32_16x16x32_bf16 v[10:13], v[156:159], v[226:229], v[10:13]
	v_mfma_f32_16x16x32_bf16 v[10:13], v[160:163], v[230:233], v[10:13]
	v_mfma_f32_16x16x32_bf16 v[26:29], v[160:163], v[222:225], v[26:29]
	v_mfma_f32_16x16x32_bf16 v[26:29], v[156:159], v[218:221], v[26:29]
	v_mfma_f32_16x16x32_bf16 v[42:45], v[156:159], v[210:213], v[42:45]
	v_mfma_f32_16x16x32_bf16 v[42:45], v[160:163], v[214:217], v[42:45]
	v_mfma_f32_16x16x32_bf16 v[58:61], v[160:163], v[184:187], v[58:61]
	v_mfma_f32_16x16x32_bf16 v[58:61], v[156:159], v[180:183], v[58:61]
	v_mfma_f32_16x16x32_bf16 v[46:49], v[172:175], v[180:183], v[46:49]
	v_mfma_f32_16x16x32_bf16 v[46:49], v[176:179], v[184:187], v[46:49]
	v_mfma_f32_16x16x32_bf16 v[30:33], v[176:179], v[214:217], v[30:33]
	v_mfma_f32_16x16x32_bf16 v[30:33], v[172:175], v[210:213], v[30:33]
	v_mfma_f32_16x16x32_bf16 v[14:17], v[172:175], v[218:221], v[14:17]
	v_mfma_f32_16x16x32_bf16 v[14:17], v[176:179], v[222:225], v[14:17]
	v_mfma_f32_16x16x32_bf16 v[2:5], v[176:179], v[230:233], v[2:5]
	v_mfma_f32_16x16x32_bf16 v[2:5], v[172:175], v[226:229], v[2:5]
	v_mfma_f32_16x16x32_bf16 v[6:9], v[164:167], v[226:229], v[6:9]
	v_mfma_f32_16x16x32_bf16 v[6:9], v[168:171], v[230:233], v[6:9]
	v_mfma_f32_16x16x32_bf16 v[22:25], v[168:171], v[222:225], v[22:25]
	v_mfma_f32_16x16x32_bf16 v[22:25], v[164:167], v[218:221], v[22:25]
	v_mfma_f32_16x16x32_bf16 v[38:41], v[164:167], v[210:213], v[38:41]
	v_mfma_f32_16x16x32_bf16 v[38:41], v[168:171], v[214:217], v[38:41]
	v_mfma_f32_16x16x32_bf16 v[54:57], v[168:171], v[184:187], v[54:57]
	v_mfma_f32_16x16x32_bf16 v[54:57], v[164:167], v[180:183], v[54:57]
	s_setprio 0
	s_barrier
	s_add_i32 s56, 0, 0x18000
	s_add_i32 s95, 0, 0x1c000
	s_add_u32 s12, s64, 0x100000
	s_addc_u32 s13, s65, 0
	s_mov_b32 m0, s85
	v_lshl_add_u64 v[246:247], s[12:13], 0, v[130:131]
	global_load_lds_dwordx4 v[246:247], off
	v_lshl_add_u64 v[246:247], s[12:13], 0, v[132:133]
	s_mov_b32 m0, s86
	s_nop 0
	global_load_lds_dwordx4 v[246:247], off
	v_add_u32_e32 v147, s56, v144
	ds_read_b128 v[148:151], v147
	ds_read_b128 v[152:155], v147 offset:1024
	ds_read_b128 v[156:159], v147 offset:2048
	ds_read_b128 v[160:163], v147 offset:3072
	v_add_u32_e32 v147, s95, v144
	ds_read_b128 v[164:167], v147
	ds_read_b128 v[168:171], v147 offset:1024
	ds_read_b128 v[172:175], v147 offset:2048
	ds_read_b128 v[176:179], v147 offset:3072
	ds_read_b128 v[180:183], v146 offset:32768
	ds_read_b128 v[184:187], v146 offset:33792
	ds_read_b128 v[210:213], v146 offset:34816
	ds_read_b128 v[214:217], v146 offset:35840
	ds_read_b128 v[218:221], v146 offset:36864
	ds_read_b128 v[222:225], v146 offset:37888
	ds_read_b128 v[226:229], v146 offset:38912
	ds_read_b128 v[230:233], v146 offset:39936
	s_waitcnt vmcnt(8)
	s_waitcnt lgkmcnt(0)
	s_barrier
	s_setprio 1
	s_waitcnt lgkmcnt(0)
	v_mfma_f32_16x16x32_bf16 v[126:129], v[148:151], v[180:183], v[126:129]
	v_mfma_f32_16x16x32_bf16 v[126:129], v[152:155], v[184:187], v[126:129]
	v_mfma_f32_16x16x32_bf16 v[114:117], v[152:155], v[214:217], v[114:117]
	v_mfma_f32_16x16x32_bf16 v[114:117], v[148:151], v[210:213], v[114:117]
	v_mfma_f32_16x16x32_bf16 v[98:101], v[148:151], v[218:221], v[98:101]
	v_mfma_f32_16x16x32_bf16 v[98:101], v[152:155], v[222:225], v[98:101]
	v_mfma_f32_16x16x32_bf16 v[82:85], v[152:155], v[230:233], v[82:85]
	v_mfma_f32_16x16x32_bf16 v[82:85], v[148:151], v[226:229], v[82:85]
	v_mfma_f32_16x16x32_bf16 v[74:77], v[156:159], v[226:229], v[74:77]
	v_mfma_f32_16x16x32_bf16 v[74:77], v[160:163], v[230:233], v[74:77]
	v_mfma_f32_16x16x32_bf16 v[90:93], v[160:163], v[222:225], v[90:93]
	v_mfma_f32_16x16x32_bf16 v[90:93], v[156:159], v[218:221], v[90:93]
	v_mfma_f32_16x16x32_bf16 v[106:109], v[156:159], v[210:213], v[106:109]
	v_mfma_f32_16x16x32_bf16 v[106:109], v[160:163], v[214:217], v[106:109]
	v_mfma_f32_16x16x32_bf16 v[122:125], v[160:163], v[184:187], v[122:125]
	v_mfma_f32_16x16x32_bf16 v[122:125], v[156:159], v[180:183], v[122:125]
	v_mfma_f32_16x16x32_bf16 v[110:113], v[172:175], v[180:183], v[110:113]
	v_mfma_f32_16x16x32_bf16 v[110:113], v[176:179], v[184:187], v[110:113]
	v_mfma_f32_16x16x32_bf16 v[94:97], v[176:179], v[214:217], v[94:97]
	v_mfma_f32_16x16x32_bf16 v[94:97], v[172:175], v[210:213], v[94:97]
	v_mfma_f32_16x16x32_bf16 v[78:81], v[172:175], v[218:221], v[78:81]
	v_mfma_f32_16x16x32_bf16 v[78:81], v[176:179], v[222:225], v[78:81]
	v_mfma_f32_16x16x32_bf16 v[66:69], v[176:179], v[230:233], v[66:69]
	v_mfma_f32_16x16x32_bf16 v[66:69], v[172:175], v[226:229], v[66:69]
	v_mfma_f32_16x16x32_bf16 v[70:73], v[164:167], v[226:229], v[70:73]
	v_mfma_f32_16x16x32_bf16 v[70:73], v[168:171], v[230:233], v[70:73]
	v_mfma_f32_16x16x32_bf16 v[86:89], v[168:171], v[222:225], v[86:89]
	v_mfma_f32_16x16x32_bf16 v[86:89], v[164:167], v[218:221], v[86:89]
	v_mfma_f32_16x16x32_bf16 v[102:105], v[164:167], v[210:213], v[102:105]
	v_mfma_f32_16x16x32_bf16 v[102:105], v[168:171], v[214:217], v[102:105]
	v_mfma_f32_16x16x32_bf16 v[118:121], v[168:171], v[184:187], v[118:121]
	v_mfma_f32_16x16x32_bf16 v[118:121], v[164:167], v[180:183], v[118:121]
	s_setprio 0
	s_barrier
	s_add_i32 s12, s56, s82
	v_lshl_add_u64 v[142:143], v[142:143], 0, s[34:35]
	s_mov_b32 m0, s12
	global_load_lds_dwordx4 v[142:143], off
	s_add_i32 m0, s12, 0x2000
	s_add_u32 s12, s62, 0x100080
	v_lshl_add_u64 v[142:143], v[188:189], 0, s[34:35]
	s_addc_u32 s13, s63, 0
	s_add_i32 s56, s95, s82
	global_load_lds_dwordx4 v[142:143], off
	v_lshl_add_u64 v[142:143], s[12:13], 0, v[190:191]
	s_mov_b32 m0, s56
	s_nop 0
	global_load_lds_dwordx4 v[142:143], off
	v_lshl_add_u64 v[142:143], s[12:13], 0, v[134:135]
	s_add_i32 m0, s56, 0x2000
	s_nop 0
	global_load_lds_dwordx4 v[142:143], off
	v_lshl_add_u64 v[142:143], v[234:235], 0, s[34:35]
	s_mov_b32 m0, s90
	s_nop 0
	global_load_lds_dwordx4 v[142:143], off
	v_lshl_add_u64 v[142:143], v[244:245], 0, s[34:35]
	s_mov_b32 m0, s97
	s_nop 0
	global_load_lds_dwordx4 v[142:143], off
	ds_read_b128 v[180:183], v146 offset:49152
	ds_read_b128 v[184:187], v146 offset:50176
	ds_read_b128 v[210:213], v146 offset:51200
	ds_read_b128 v[214:217], v146 offset:52224
	ds_read_b128 v[218:221], v146 offset:53248
	ds_read_b128 v[222:225], v146 offset:54272
	ds_read_b128 v[226:229], v146 offset:55296
	ds_read_b128 v[230:233], v146 offset:56320
	s_waitcnt vmcnt(8)
	s_waitcnt lgkmcnt(0)
	s_barrier
	s_setprio 1
	s_waitcnt lgkmcnt(0)
	v_mfma_f32_16x16x32_bf16 v[62:65], v[148:151], v[180:183], v[62:65]
	v_mfma_f32_16x16x32_bf16 v[62:65], v[152:155], v[184:187], v[62:65]
	v_mfma_f32_16x16x32_bf16 v[50:53], v[152:155], v[214:217], v[50:53]
	v_mfma_f32_16x16x32_bf16 v[50:53], v[148:151], v[210:213], v[50:53]
	v_mfma_f32_16x16x32_bf16 v[34:37], v[148:151], v[218:221], v[34:37]
	v_mfma_f32_16x16x32_bf16 v[34:37], v[152:155], v[222:225], v[34:37]
	v_mfma_f32_16x16x32_bf16 v[18:21], v[152:155], v[230:233], v[18:21]
	v_mfma_f32_16x16x32_bf16 v[18:21], v[148:151], v[226:229], v[18:21]
	v_mfma_f32_16x16x32_bf16 v[10:13], v[156:159], v[226:229], v[10:13]
	v_mfma_f32_16x16x32_bf16 v[10:13], v[160:163], v[230:233], v[10:13]
	v_mfma_f32_16x16x32_bf16 v[26:29], v[160:163], v[222:225], v[26:29]
	v_mfma_f32_16x16x32_bf16 v[26:29], v[156:159], v[218:221], v[26:29]
	v_mfma_f32_16x16x32_bf16 v[42:45], v[156:159], v[210:213], v[42:45]
	v_mfma_f32_16x16x32_bf16 v[42:45], v[160:163], v[214:217], v[42:45]
	v_mfma_f32_16x16x32_bf16 v[58:61], v[160:163], v[184:187], v[58:61]
	v_mfma_f32_16x16x32_bf16 v[58:61], v[156:159], v[180:183], v[58:61]
	v_mfma_f32_16x16x32_bf16 v[46:49], v[172:175], v[180:183], v[46:49]
	v_mfma_f32_16x16x32_bf16 v[46:49], v[176:179], v[184:187], v[46:49]
	v_mfma_f32_16x16x32_bf16 v[30:33], v[176:179], v[214:217], v[30:33]
	v_mfma_f32_16x16x32_bf16 v[30:33], v[172:175], v[210:213], v[30:33]
	v_mfma_f32_16x16x32_bf16 v[14:17], v[172:175], v[218:221], v[14:17]
	v_mfma_f32_16x16x32_bf16 v[14:17], v[176:179], v[222:225], v[14:17]
	v_mfma_f32_16x16x32_bf16 v[2:5], v[176:179], v[230:233], v[2:5]
	v_mfma_f32_16x16x32_bf16 v[2:5], v[172:175], v[226:229], v[2:5]
	v_mfma_f32_16x16x32_bf16 v[6:9], v[164:167], v[226:229], v[6:9]
	v_mfma_f32_16x16x32_bf16 v[6:9], v[168:171], v[230:233], v[6:9]
	v_mfma_f32_16x16x32_bf16 v[22:25], v[168:171], v[222:225], v[22:25]
	v_mfma_f32_16x16x32_bf16 v[22:25], v[164:167], v[218:221], v[22:25]
	v_mfma_f32_16x16x32_bf16 v[38:41], v[164:167], v[210:213], v[38:41]
	v_mfma_f32_16x16x32_bf16 v[38:41], v[168:171], v[214:217], v[38:41]
	v_mfma_f32_16x16x32_bf16 v[54:57], v[168:171], v[184:187], v[54:57]
	v_mfma_f32_16x16x32_bf16 v[54:57], v[164:167], v[180:183], v[54:57]
	s_setprio 0
	s_barrier
	s_add_i32 s94, s94, 2
	s_add_u32 s54, s54, 0x100
	s_addc_u32 s55, s55, 0
	s_add_u32 vcc_hi, vcc_hi, 0x100
	s_addc_u32 s61, s61, 0
	s_cmp_gt_u32 s94, 61
	s_cbranch_scc0 .LBB0_252
	s_and_b64 vcc, exec, s[42:43]
	s_cbranch_vccz .LBB0_255
	s_barrier

.LBB0_692:
	s_add_u32 s12, s40, 0xfffc0080
	s_addc_u32 s13, s41, -1
	s_add_i32 s56, 0, 0x10000
	s_cmp_eq_u32 s74, 12
	s_cselect_b32 s63, s47, s13
	s_cselect_b32 s62, s71, s12
	s_cselect_b32 s55, s45, s61
	s_cselect_b32 s54, s72, s73
	s_add_i32 s75, 0, 0x14000
	v_lshl_add_u64 v[188:189], s[40:41], 0, v[152:153]
	s_add_i32 m0, s53, 0xc000
	global_load_lds_dwordx4 v[188:189], off
	v_lshl_add_u64 v[188:189], s[40:41], 0, v[154:155]
	s_add_i32 m0, s53, 0xe000
	s_nop 0
	global_load_lds_dwordx4 v[188:189], off
	v_add_u32_e32 v142, s56, v160
	v_add_u32_e32 v163, s75, v160
	ds_read_b128 v[130:133], v142
	ds_read_b128 v[134:137], v142 offset:1024
	ds_read_b128 v[138:141], v142 offset:2048
	ds_read_b128 v[142:145], v142 offset:3072
	ds_read_b128 v[156:159], v163
	ds_read_b128 v[164:167], v163 offset:1024
	ds_read_b128 v[168:171], v163 offset:2048
	ds_read_b128 v[172:175], v163 offset:3072
	ds_read_b128 v[176:179], v162
	ds_read_b128 v[180:183], v162 offset:1024
	ds_read_b128 v[184:187], v162 offset:2048
	ds_read_b128 v[210:213], v162 offset:3072
	ds_read_b128 v[214:217], v162 offset:4096
	ds_read_b128 v[218:221], v162 offset:5120
	ds_read_b128 v[222:225], v162 offset:6144
	ds_read_b128 v[226:229], v162 offset:7168
	s_waitcnt vmcnt(8)
	s_waitcnt lgkmcnt(0)
	s_barrier
	s_setprio 1
	s_waitcnt lgkmcnt(0)
	v_mfma_f32_16x16x32_bf16 v[126:129], v[130:133], v[176:179], v[126:129]
	v_mfma_f32_16x16x32_bf16 v[126:129], v[134:137], v[180:183], v[126:129]
	v_mfma_f32_16x16x32_bf16 v[114:117], v[134:137], v[210:213], v[114:117]
	v_mfma_f32_16x16x32_bf16 v[114:117], v[130:133], v[184:187], v[114:117]
	v_mfma_f32_16x16x32_bf16 v[98:101], v[130:133], v[214:217], v[98:101]
	v_mfma_f32_16x16x32_bf16 v[98:101], v[134:137], v[218:221], v[98:101]
	v_mfma_f32_16x16x32_bf16 v[82:85], v[134:137], v[226:229], v[82:85]
	v_mfma_f32_16x16x32_bf16 v[82:85], v[130:133], v[222:225], v[82:85]
	v_mfma_f32_16x16x32_bf16 v[74:77], v[138:141], v[222:225], v[74:77]
	v_mfma_f32_16x16x32_bf16 v[74:77], v[142:145], v[226:229], v[74:77]
	v_mfma_f32_16x16x32_bf16 v[90:93], v[142:145], v[218:221], v[90:93]
	v_mfma_f32_16x16x32_bf16 v[90:93], v[138:141], v[214:217], v[90:93]
	v_mfma_f32_16x16x32_bf16 v[106:109], v[138:141], v[184:187], v[106:109]
	v_mfma_f32_16x16x32_bf16 v[106:109], v[142:145], v[210:213], v[106:109]
	v_mfma_f32_16x16x32_bf16 v[122:125], v[142:145], v[180:183], v[122:125]
	v_mfma_f32_16x16x32_bf16 v[122:125], v[138:141], v[176:179], v[122:125]
	v_mfma_f32_16x16x32_bf16 v[110:113], v[168:171], v[176:179], v[110:113]
	v_mfma_f32_16x16x32_bf16 v[110:113], v[172:175], v[180:183], v[110:113]
	v_mfma_f32_16x16x32_bf16 v[94:97], v[172:175], v[210:213], v[94:97]
	v_mfma_f32_16x16x32_bf16 v[94:97], v[168:171], v[184:187], v[94:97]
	v_mfma_f32_16x16x32_bf16 v[78:81], v[168:171], v[214:217], v[78:81]
	v_mfma_f32_16x16x32_bf16 v[78:81], v[172:175], v[218:221], v[78:81]
	v_mfma_f32_16x16x32_bf16 v[66:69], v[172:175], v[226:229], v[66:69]
	v_mfma_f32_16x16x32_bf16 v[66:69], v[168:171], v[222:225], v[66:69]
	v_mfma_f32_16x16x32_bf16 v[70:73], v[156:159], v[222:225], v[70:73]
	v_mfma_f32_16x16x32_bf16 v[70:73], v[164:167], v[226:229], v[70:73]
	v_mfma_f32_16x16x32_bf16 v[86:89], v[164:167], v[218:221], v[86:89]
	v_mfma_f32_16x16x32_bf16 v[86:89], v[156:159], v[214:217], v[86:89]
	v_mfma_f32_16x16x32_bf16 v[102:105], v[156:159], v[184:187], v[102:105]
	v_mfma_f32_16x16x32_bf16 v[102:105], v[164:167], v[210:213], v[102:105]
	v_mfma_f32_16x16x32_bf16 v[118:121], v[164:167], v[180:183], v[118:121]
	v_mfma_f32_16x16x32_bf16 v[118:121], v[156:159], v[176:179], v[118:121]
	s_setprio 0
	s_barrier
	s_add_i32 s12, s56, s59
	v_lshl_add_u64 v[188:189], s[54:55], 0, v[190:191]
	s_mov_b32 m0, s12
	global_load_lds_dwordx4 v[188:189], off
	s_add_i32 m0, s12, 0x2000
	s_add_u32 s12, s54, 0x40000
	v_lshl_add_u64 v[230:231], s[54:55], 0, v[150:151]
	s_addc_u32 s13, s55, 0
	s_add_i32 s56, s75, s59
	global_load_lds_dwordx4 v[230:231], off
	v_lshl_add_u64 v[232:233], s[12:13], 0, v[190:191]
	s_mov_b32 m0, s56
	v_lshl_add_u64 v[234:235], s[62:63], 0, v[148:149]
	global_load_lds_dwordx4 v[232:233], off
	v_lshl_add_u64 v[232:233], s[12:13], 0, v[150:151]
	s_add_i32 m0, s56, 0x2000
	s_nop 0
	global_load_lds_dwordx4 v[232:233], off
	v_lshl_add_u64 v[232:233], s[62:63], 0, v[146:147]
	s_mov_b32 m0, s53
	s_nop 0
	global_load_lds_dwordx4 v[232:233], off
	s_mov_b32 m0, s60
	s_nop 0
	global_load_lds_dwordx4 v[234:235], off
	ds_read_b128 v[176:179], v162 offset:16384
	ds_read_b128 v[180:183], v162 offset:17408
	ds_read_b128 v[184:187], v162 offset:18432
	ds_read_b128 v[210:213], v162 offset:19456
	ds_read_b128 v[214:217], v162 offset:20480
	ds_read_b128 v[218:221], v162 offset:21504
	ds_read_b128 v[222:225], v162 offset:22528
	ds_read_b128 v[226:229], v162 offset:23552
	s_waitcnt vmcnt(8)
	s_waitcnt lgkmcnt(0)
	s_barrier
	s_setprio 1
	s_waitcnt lgkmcnt(0)
	v_mfma_f32_16x16x32_bf16 v[62:65], v[130:133], v[176:179], v[62:65]
	v_mfma_f32_16x16x32_bf16 v[62:65], v[134:137], v[180:183], v[62:65]
	v_mfma_f32_16x16x32_bf16 v[50:53], v[134:137], v[210:213], v[50:53]
	v_mfma_f32_16x16x32_bf16 v[50:53], v[130:133], v[184:187], v[50:53]
	v_mfma_f32_16x16x32_bf16 v[34:37], v[130:133], v[214:217], v[34:37]
	v_mfma_f32_16x16x32_bf16 v[34:37], v[134:137], v[218:221], v[34:37]
	v_mfma_f32_16x16x32_bf16 v[18:21], v[134:137], v[226:229], v[18:21]
	v_mfma_f32_16x16x32_bf16 v[18:21], v[130:133], v[222:225], v[18:21]
	v_mfma_f32_16x16x32_bf16 v[10:13], v[138:141], v[222:225], v[10:13]
	v_mfma_f32_16x16x32_bf16 v[10:13], v[142:145], v[226:229], v[10:13]
	v_mfma_f32_16x16x32_bf16 v[26:29], v[142:145], v[218:221], v[26:29]
	v_mfma_f32_16x16x32_bf16 v[26:29], v[138:141], v[214:217], v[26:29]
	v_mfma_f32_16x16x32_bf16 v[42:45], v[138:141], v[184:187], v[42:45]
	v_mfma_f32_16x16x32_bf16 v[42:45], v[142:145], v[210:213], v[42:45]
	v_mfma_f32_16x16x32_bf16 v[58:61], v[142:145], v[180:183], v[58:61]
	v_mfma_f32_16x16x32_bf16 v[58:61], v[138:141], v[176:179], v[58:61]
	v_mfma_f32_16x16x32_bf16 v[46:49], v[168:171], v[176:179], v[46:49]
	v_mfma_f32_16x16x32_bf16 v[46:49], v[172:175], v[180:183], v[46:49]
	v_mfma_f32_16x16x32_bf16 v[30:33], v[172:175], v[210:213], v[30:33]
	v_mfma_f32_16x16x32_bf16 v[30:33], v[168:171], v[184:187], v[30:33]
	v_mfma_f32_16x16x32_bf16 v[14:17], v[168:171], v[214:217], v[14:17]
	v_mfma_f32_16x16x32_bf16 v[14:17], v[172:175], v[218:221], v[14:17]
	v_mfma_f32_16x16x32_bf16 v[2:5], v[172:175], v[226:229], v[2:5]
	v_mfma_f32_16x16x32_bf16 v[2:5], v[168:171], v[222:225], v[2:5]
	v_mfma_f32_16x16x32_bf16 v[6:9], v[156:159], v[222:225], v[6:9]
	v_mfma_f32_16x16x32_bf16 v[6:9], v[164:167], v[226:229], v[6:9]
	v_mfma_f32_16x16x32_bf16 v[22:25], v[164:167], v[218:221], v[22:25]
	v_mfma_f32_16x16x32_bf16 v[22:25], v[156:159], v[214:217], v[22:25]
	v_mfma_f32_16x16x32_bf16 v[38:41], v[156:159], v[184:187], v[38:41]
	v_mfma_f32_16x16x32_bf16 v[38:41], v[164:167], v[210:213], v[38:41]
	v_mfma_f32_16x16x32_bf16 v[54:57], v[164:167], v[180:183], v[54:57]
	v_mfma_f32_16x16x32_bf16 v[54:57], v[156:159], v[176:179], v[54:57]
	s_setprio 0
	s_barrier
	s_add_i32 s56, 0, 0x18000
	s_add_i32 s75, 0, 0x1c000
	s_add_u32 s12, s62, 0x40000
	s_addc_u32 s13, s63, 0
	s_mov_b32 m0, s64
	v_lshl_add_u64 v[244:245], s[12:13], 0, v[146:147]
	global_load_lds_dwordx4 v[244:245], off
	v_lshl_add_u64 v[244:245], s[12:13], 0, v[148:149]
	s_mov_b32 m0, s65
	s_nop 0
	global_load_lds_dwordx4 v[244:245], off
	v_add_u32_e32 v142, s56, v160
	v_add_u32_e32 v163, s75, v160
	ds_read_b128 v[130:133], v142
	ds_read_b128 v[134:137], v142 offset:1024
	ds_read_b128 v[138:141], v142 offset:2048
	ds_read_b128 v[142:145], v142 offset:3072
	ds_read_b128 v[156:159], v163
	ds_read_b128 v[164:167], v163 offset:1024
	ds_read_b128 v[168:171], v163 offset:2048
	ds_read_b128 v[172:175], v163 offset:3072
	ds_read_b128 v[176:179], v162 offset:32768
	ds_read_b128 v[180:183], v162 offset:33792
	ds_read_b128 v[184:187], v162 offset:34816
	ds_read_b128 v[210:213], v162 offset:35840
	ds_read_b128 v[214:217], v162 offset:36864
	ds_read_b128 v[218:221], v162 offset:37888
	ds_read_b128 v[222:225], v162 offset:38912
	ds_read_b128 v[226:229], v162 offset:39936
	s_waitcnt vmcnt(8)
	s_waitcnt lgkmcnt(0)
	s_barrier
	s_setprio 1
	s_waitcnt lgkmcnt(0)
	v_mfma_f32_16x16x32_bf16 v[126:129], v[130:133], v[176:179], v[126:129]
	v_mfma_f32_16x16x32_bf16 v[126:129], v[134:137], v[180:183], v[126:129]
	v_mfma_f32_16x16x32_bf16 v[114:117], v[134:137], v[210:213], v[114:117]
	v_mfma_f32_16x16x32_bf16 v[114:117], v[130:133], v[184:187], v[114:117]
	v_mfma_f32_16x16x32_bf16 v[98:101], v[130:133], v[214:217], v[98:101]
	v_mfma_f32_16x16x32_bf16 v[98:101], v[134:137], v[218:221], v[98:101]
	v_mfma_f32_16x16x32_bf16 v[82:85], v[134:137], v[226:229], v[82:85]
	v_mfma_f32_16x16x32_bf16 v[82:85], v[130:133], v[222:225], v[82:85]
	v_mfma_f32_16x16x32_bf16 v[74:77], v[138:141], v[222:225], v[74:77]
	v_mfma_f32_16x16x32_bf16 v[74:77], v[142:145], v[226:229], v[74:77]
	v_mfma_f32_16x16x32_bf16 v[90:93], v[142:145], v[218:221], v[90:93]
	v_mfma_f32_16x16x32_bf16 v[90:93], v[138:141], v[214:217], v[90:93]
	v_mfma_f32_16x16x32_bf16 v[106:109], v[138:141], v[184:187], v[106:109]
	v_mfma_f32_16x16x32_bf16 v[106:109], v[142:145], v[210:213], v[106:109]
	v_mfma_f32_16x16x32_bf16 v[122:125], v[142:145], v[180:183], v[122:125]
	v_mfma_f32_16x16x32_bf16 v[122:125], v[138:141], v[176:179], v[122:125]
	v_mfma_f32_16x16x32_bf16 v[110:113], v[168:171], v[176:179], v[110:113]
	v_mfma_f32_16x16x32_bf16 v[110:113], v[172:175], v[180:183], v[110:113]
	v_mfma_f32_16x16x32_bf16 v[94:97], v[172:175], v[210:213], v[94:97]
	v_mfma_f32_16x16x32_bf16 v[94:97], v[168:171], v[184:187], v[94:97]
	v_mfma_f32_16x16x32_bf16 v[78:81], v[168:171], v[214:217], v[78:81]
	v_mfma_f32_16x16x32_bf16 v[78:81], v[172:175], v[218:221], v[78:81]
	v_mfma_f32_16x16x32_bf16 v[66:69], v[172:175], v[226:229], v[66:69]
	v_mfma_f32_16x16x32_bf16 v[66:69], v[168:171], v[222:225], v[66:69]
	v_mfma_f32_16x16x32_bf16 v[70:73], v[156:159], v[222:225], v[70:73]
	v_mfma_f32_16x16x32_bf16 v[70:73], v[164:167], v[226:229], v[70:73]
	v_mfma_f32_16x16x32_bf16 v[86:89], v[164:167], v[218:221], v[86:89]
	v_mfma_f32_16x16x32_bf16 v[86:89], v[156:159], v[214:217], v[86:89]
	v_mfma_f32_16x16x32_bf16 v[102:105], v[156:159], v[184:187], v[102:105]
	v_mfma_f32_16x16x32_bf16 v[102:105], v[164:167], v[210:213], v[102:105]
	v_mfma_f32_16x16x32_bf16 v[118:121], v[164:167], v[180:183], v[118:121]
	v_mfma_f32_16x16x32_bf16 v[118:121], v[156:159], v[176:179], v[118:121]
	s_setprio 0
	s_barrier
	s_add_i32 s12, s56, s59
	v_lshl_add_u64 v[188:189], v[188:189], 0, s[34:35]
	s_mov_b32 m0, s12
	global_load_lds_dwordx4 v[188:189], off
	s_add_i32 m0, s12, 0x2000
	s_add_u32 s12, s54, 0x40080
	v_lshl_add_u64 v[188:189], v[230:231], 0, s[34:35]
	s_addc_u32 s13, s55, 0
	s_add_i32 s54, s75, s59
	global_load_lds_dwordx4 v[188:189], off
	v_lshl_add_u64 v[188:189], s[12:13], 0, v[190:191]
	s_mov_b32 m0, s54
	s_nop 0
	global_load_lds_dwordx4 v[188:189], off
	v_lshl_add_u64 v[188:189], s[12:13], 0, v[150:151]
	s_add_i32 m0, s54, 0x2000
	s_nop 0
	global_load_lds_dwordx4 v[188:189], off
	v_lshl_add_u64 v[188:189], v[232:233], 0, s[34:35]
	s_mov_b32 m0, s66
	s_nop 0
	global_load_lds_dwordx4 v[188:189], off
	v_lshl_add_u64 v[188:189], v[234:235], 0, s[34:35]
	s_mov_b32 m0, s68
	s_nop 0
	global_load_lds_dwordx4 v[188:189], off
	ds_read_b128 v[176:179], v162 offset:49152
	ds_read_b128 v[180:183], v162 offset:50176
	ds_read_b128 v[184:187], v162 offset:51200
	ds_read_b128 v[210:213], v162 offset:52224
	ds_read_b128 v[214:217], v162 offset:53248
	ds_read_b128 v[218:221], v162 offset:54272
	ds_read_b128 v[222:225], v162 offset:55296
	ds_read_b128 v[226:229], v162 offset:56320
	s_waitcnt vmcnt(8)
	s_waitcnt lgkmcnt(0)
	s_barrier
	s_setprio 1
	s_waitcnt lgkmcnt(0)
	v_mfma_f32_16x16x32_bf16 v[62:65], v[130:133], v[176:179], v[62:65]
	v_mfma_f32_16x16x32_bf16 v[62:65], v[134:137], v[180:183], v[62:65]
	v_mfma_f32_16x16x32_bf16 v[50:53], v[134:137], v[210:213], v[50:53]
	v_mfma_f32_16x16x32_bf16 v[50:53], v[130:133], v[184:187], v[50:53]
	v_mfma_f32_16x16x32_bf16 v[34:37], v[130:133], v[214:217], v[34:37]
	v_mfma_f32_16x16x32_bf16 v[34:37], v[134:137], v[218:221], v[34:37]
	v_mfma_f32_16x16x32_bf16 v[18:21], v[134:137], v[226:229], v[18:21]
	v_mfma_f32_16x16x32_bf16 v[18:21], v[130:133], v[222:225], v[18:21]
	v_mfma_f32_16x16x32_bf16 v[10:13], v[138:141], v[222:225], v[10:13]
	v_mfma_f32_16x16x32_bf16 v[10:13], v[142:145], v[226:229], v[10:13]
	v_mfma_f32_16x16x32_bf16 v[26:29], v[142:145], v[218:221], v[26:29]
	v_mfma_f32_16x16x32_bf16 v[26:29], v[138:141], v[214:217], v[26:29]
	v_mfma_f32_16x16x32_bf16 v[42:45], v[138:141], v[184:187], v[42:45]
	v_mfma_f32_16x16x32_bf16 v[42:45], v[142:145], v[210:213], v[42:45]
	v_mfma_f32_16x16x32_bf16 v[58:61], v[142:145], v[180:183], v[58:61]
	v_mfma_f32_16x16x32_bf16 v[58:61], v[138:141], v[176:179], v[58:61]
	v_mfma_f32_16x16x32_bf16 v[46:49], v[168:171], v[176:179], v[46:49]
	v_mfma_f32_16x16x32_bf16 v[46:49], v[172:175], v[180:183], v[46:49]
	v_mfma_f32_16x16x32_bf16 v[30:33], v[172:175], v[210:213], v[30:33]
	v_mfma_f32_16x16x32_bf16 v[30:33], v[168:171], v[184:187], v[30:33]
	v_mfma_f32_16x16x32_bf16 v[14:17], v[168:171], v[214:217], v[14:17]
	v_mfma_f32_16x16x32_bf16 v[14:17], v[172:175], v[218:221], v[14:17]
	v_mfma_f32_16x16x32_bf16 v[2:5], v[172:175], v[226:229], v[2:5]
	v_mfma_f32_16x16x32_bf16 v[2:5], v[168:171], v[222:225], v[2:5]
	v_mfma_f32_16x16x32_bf16 v[6:9], v[156:159], v[222:225], v[6:9]
	v_mfma_f32_16x16x32_bf16 v[6:9], v[164:167], v[226:229], v[6:9]
	v_mfma_f32_16x16x32_bf16 v[22:25], v[164:167], v[218:221], v[22:25]
	v_mfma_f32_16x16x32_bf16 v[22:25], v[156:159], v[214:217], v[22:25]
	v_mfma_f32_16x16x32_bf16 v[38:41], v[156:159], v[184:187], v[38:41]
	v_mfma_f32_16x16x32_bf16 v[38:41], v[164:167], v[210:213], v[38:41]
	v_mfma_f32_16x16x32_bf16 v[54:57], v[164:167], v[180:183], v[54:57]
	v_mfma_f32_16x16x32_bf16 v[54:57], v[156:159], v[176:179], v[54:57]
	s_setprio 0
	s_barrier
	s_add_i32 s74, s74, 2
	s_add_u32 s40, s40, 0x100
	s_addc_u32 s41, s41, 0
	s_add_u32 s73, s73, 0x100
	s_addc_u32 s61, s61, 0
	s_cmp_gt_u32 s74, 13
	s_cbranch_scc0 .LBB0_692
	s_and_b64 vcc, exec, s[30:31]
	s_cbranch_vccz .LBB0_695
	s_barrier

.LBB0_777:
	s_add_u32 s12, s50, 0xfff00080
	s_addc_u32 s13, s51, -1
	s_add_i32 s56, 0, 0x10000
	s_cmp_eq_u32 s72, 60
	s_cselect_b32 s55, s43, s13
	s_cselect_b32 s54, s49, s12
	s_cselect_b32 s53, s41, s61
	s_cselect_b32 s52, s70, s71
	s_add_i32 s73, 0, 0x14000
	v_lshl_add_u64 v[224:225], s[50:51], 0, v[216:217]
	s_add_i32 m0, s33, 0xc000
	global_load_lds_dwordx4 v[224:225], off
	v_lshl_add_u64 v[224:225], s[50:51], 0, v[218:219]
	s_add_i32 m0, s33, 0xe000
	s_nop 0
	global_load_lds_dwordx4 v[224:225], off
	v_add_u32_e32 v142, s56, v193
	v_add_u32_e32 v158, s73, v193
	ds_read_b128 v[130:133], v142
	ds_read_b128 v[134:137], v142 offset:1024
	ds_read_b128 v[138:141], v142 offset:2048
	ds_read_b128 v[142:145], v142 offset:3072
	ds_read_b128 v[146:149], v158
	ds_read_b128 v[150:153], v158 offset:1024
	ds_read_b128 v[154:157], v158 offset:2048
	ds_read_b128 v[158:161], v158 offset:3072
	ds_read_b128 v[162:165], v197
	ds_read_b128 v[166:169], v197 offset:1024
	ds_read_b128 v[170:173], v197 offset:2048
	ds_read_b128 v[174:177], v197 offset:3072
	ds_read_b128 v[178:181], v197 offset:4096
	ds_read_b128 v[182:185], v197 offset:5120
	ds_read_b128 v[186:189], v197 offset:6144
	ds_read_b128 v[220:223], v197 offset:7168
	s_waitcnt vmcnt(8)
	s_waitcnt lgkmcnt(0)
	s_barrier
	s_setprio 1
	s_waitcnt lgkmcnt(0)
	v_mfma_f32_16x16x32_bf16 v[126:129], v[130:133], v[162:165], v[126:129]
	v_mfma_f32_16x16x32_bf16 v[126:129], v[134:137], v[166:169], v[126:129]
	v_mfma_f32_16x16x32_bf16 v[110:113], v[134:137], v[174:177], v[110:113]
	v_mfma_f32_16x16x32_bf16 v[110:113], v[130:133], v[170:173], v[110:113]
	v_mfma_f32_16x16x32_bf16 v[98:101], v[130:133], v[178:181], v[98:101]
	v_mfma_f32_16x16x32_bf16 v[98:101], v[134:137], v[182:185], v[98:101]
	v_mfma_f32_16x16x32_bf16 v[82:85], v[134:137], v[220:223], v[82:85]
	v_mfma_f32_16x16x32_bf16 v[82:85], v[130:133], v[186:189], v[82:85]
	v_mfma_f32_16x16x32_bf16 v[74:77], v[138:141], v[186:189], v[74:77]
	v_mfma_f32_16x16x32_bf16 v[74:77], v[142:145], v[220:223], v[74:77]
	v_mfma_f32_16x16x32_bf16 v[90:93], v[142:145], v[182:185], v[90:93]
	v_mfma_f32_16x16x32_bf16 v[90:93], v[138:141], v[178:181], v[90:93]
	v_mfma_f32_16x16x32_bf16 v[106:109], v[138:141], v[170:173], v[106:109]
	v_mfma_f32_16x16x32_bf16 v[106:109], v[142:145], v[174:177], v[106:109]
	v_mfma_f32_16x16x32_bf16 v[122:125], v[142:145], v[166:169], v[122:125]
	v_mfma_f32_16x16x32_bf16 v[122:125], v[138:141], v[162:165], v[122:125]
	v_mfma_f32_16x16x32_bf16 v[114:117], v[154:157], v[162:165], v[114:117]
	v_mfma_f32_16x16x32_bf16 v[114:117], v[158:161], v[166:169], v[114:117]
	v_mfma_f32_16x16x32_bf16 v[94:97], v[158:161], v[174:177], v[94:97]
	v_mfma_f32_16x16x32_bf16 v[94:97], v[154:157], v[170:173], v[94:97]
	v_mfma_f32_16x16x32_bf16 v[78:81], v[154:157], v[178:181], v[78:81]
	v_mfma_f32_16x16x32_bf16 v[78:81], v[158:161], v[182:185], v[78:81]
	v_mfma_f32_16x16x32_bf16 v[66:69], v[158:161], v[220:223], v[66:69]
	v_mfma_f32_16x16x32_bf16 v[66:69], v[154:157], v[186:189], v[66:69]
	v_mfma_f32_16x16x32_bf16 v[70:73], v[146:149], v[186:189], v[70:73]
	v_mfma_f32_16x16x32_bf16 v[70:73], v[150:153], v[220:223], v[70:73]
	v_mfma_f32_16x16x32_bf16 v[86:89], v[150:153], v[182:185], v[86:89]
	v_mfma_f32_16x16x32_bf16 v[86:89], v[146:149], v[178:181], v[86:89]
	v_mfma_f32_16x16x32_bf16 v[102:105], v[146:149], v[170:173], v[102:105]
	v_mfma_f32_16x16x32_bf16 v[102:105], v[150:153], v[174:177], v[102:105]
	v_mfma_f32_16x16x32_bf16 v[118:121], v[150:153], v[166:169], v[118:121]
	v_mfma_f32_16x16x32_bf16 v[118:121], v[146:149], v[162:165], v[118:121]
	s_setprio 0
	s_barrier
	s_add_i32 s12, s56, s29
	v_lshl_add_u64 v[224:225], s[52:53], 0, v[190:191]
	s_mov_b32 m0, s12
	global_load_lds_dwordx4 v[224:225], off
	s_add_i32 m0, s12, 0x2000
	s_add_u32 s12, s52, 0x100000
	v_lshl_add_u64 v[226:227], s[52:53], 0, v[214:215]
	s_addc_u32 s13, s53, 0
	s_add_i32 s56, s73, s29
	global_load_lds_dwordx4 v[226:227], off
	v_lshl_add_u64 v[228:229], s[12:13], 0, v[190:191]
	s_mov_b32 m0, s56
	v_lshl_add_u64 v[230:231], s[54:55], 0, v[212:213]
	global_load_lds_dwordx4 v[228:229], off
	v_lshl_add_u64 v[228:229], s[12:13], 0, v[214:215]
	s_add_i32 m0, s56, 0x2000
	s_nop 0
	global_load_lds_dwordx4 v[228:229], off
	v_lshl_add_u64 v[228:229], s[54:55], 0, v[210:211]
	s_mov_b32 m0, s33
	s_nop 0
	global_load_lds_dwordx4 v[228:229], off
	s_mov_b32 m0, s62
	s_nop 0
	global_load_lds_dwordx4 v[230:231], off
	ds_read_b128 v[162:165], v197 offset:16384
	ds_read_b128 v[166:169], v197 offset:17408
	ds_read_b128 v[170:173], v197 offset:18432
	ds_read_b128 v[174:177], v197 offset:19456
	ds_read_b128 v[178:181], v197 offset:20480
	ds_read_b128 v[182:185], v197 offset:21504
	ds_read_b128 v[186:189], v197 offset:22528
	ds_read_b128 v[220:223], v197 offset:23552
	s_waitcnt vmcnt(8)
	s_waitcnt lgkmcnt(0)
	s_barrier
	s_setprio 1
	s_waitcnt lgkmcnt(0)
	v_mfma_f32_16x16x32_bf16 v[62:65], v[130:133], v[162:165], v[62:65]
	v_mfma_f32_16x16x32_bf16 v[62:65], v[134:137], v[166:169], v[62:65]
	v_mfma_f32_16x16x32_bf16 v[50:53], v[134:137], v[174:177], v[50:53]
	v_mfma_f32_16x16x32_bf16 v[50:53], v[130:133], v[170:173], v[50:53]
	v_mfma_f32_16x16x32_bf16 v[34:37], v[130:133], v[178:181], v[34:37]
	v_mfma_f32_16x16x32_bf16 v[34:37], v[134:137], v[182:185], v[34:37]
	v_mfma_f32_16x16x32_bf16 v[18:21], v[134:137], v[220:223], v[18:21]
	v_mfma_f32_16x16x32_bf16 v[18:21], v[130:133], v[186:189], v[18:21]
	v_mfma_f32_16x16x32_bf16 v[10:13], v[138:141], v[186:189], v[10:13]
	v_mfma_f32_16x16x32_bf16 v[10:13], v[142:145], v[220:223], v[10:13]
	v_mfma_f32_16x16x32_bf16 v[26:29], v[142:145], v[182:185], v[26:29]
	v_mfma_f32_16x16x32_bf16 v[26:29], v[138:141], v[178:181], v[26:29]
	v_mfma_f32_16x16x32_bf16 v[42:45], v[138:141], v[170:173], v[42:45]
	v_mfma_f32_16x16x32_bf16 v[42:45], v[142:145], v[174:177], v[42:45]
	v_mfma_f32_16x16x32_bf16 v[58:61], v[142:145], v[166:169], v[58:61]
	v_mfma_f32_16x16x32_bf16 v[58:61], v[138:141], v[162:165], v[58:61]
	v_mfma_f32_16x16x32_bf16 v[46:49], v[154:157], v[162:165], v[46:49]
	v_mfma_f32_16x16x32_bf16 v[46:49], v[158:161], v[166:169], v[46:49]
	v_mfma_f32_16x16x32_bf16 v[30:33], v[158:161], v[174:177], v[30:33]
	v_mfma_f32_16x16x32_bf16 v[30:33], v[154:157], v[170:173], v[30:33]
	v_mfma_f32_16x16x32_bf16 v[14:17], v[154:157], v[178:181], v[14:17]
	v_mfma_f32_16x16x32_bf16 v[14:17], v[158:161], v[182:185], v[14:17]
	v_mfma_f32_16x16x32_bf16 v[2:5], v[158:161], v[220:223], v[2:5]
	v_mfma_f32_16x16x32_bf16 v[2:5], v[154:157], v[186:189], v[2:5]
	v_mfma_f32_16x16x32_bf16 v[6:9], v[146:149], v[186:189], v[6:9]
	v_mfma_f32_16x16x32_bf16 v[6:9], v[150:153], v[220:223], v[6:9]
	v_mfma_f32_16x16x32_bf16 v[22:25], v[150:153], v[182:185], v[22:25]
	v_mfma_f32_16x16x32_bf16 v[22:25], v[146:149], v[178:181], v[22:25]
	v_mfma_f32_16x16x32_bf16 v[38:41], v[146:149], v[170:173], v[38:41]
	v_mfma_f32_16x16x32_bf16 v[38:41], v[150:153], v[174:177], v[38:41]
	v_mfma_f32_16x16x32_bf16 v[54:57], v[150:153], v[166:169], v[54:57]
	v_mfma_f32_16x16x32_bf16 v[54:57], v[146:149], v[162:165], v[54:57]
	s_setprio 0
	s_barrier
	s_add_i32 s56, 0, 0x18000
	s_add_i32 s73, 0, 0x1c000
	s_add_u32 s12, s54, 0x100000
	s_addc_u32 s13, s55, 0
	s_mov_b32 m0, s63
	v_lshl_add_u64 v[232:233], s[12:13], 0, v[210:211]
	global_load_lds_dwordx4 v[232:233], off
	v_lshl_add_u64 v[232:233], s[12:13], 0, v[212:213]
	s_mov_b32 m0, s64
	s_nop 0
	global_load_lds_dwordx4 v[232:233], off
	v_add_u32_e32 v142, s56, v193
	v_add_u32_e32 v158, s73, v193
	ds_read_b128 v[130:133], v142
	ds_read_b128 v[134:137], v142 offset:1024
	ds_read_b128 v[138:141], v142 offset:2048
	ds_read_b128 v[142:145], v142 offset:3072
	ds_read_b128 v[146:149], v158
	ds_read_b128 v[150:153], v158 offset:1024
	ds_read_b128 v[154:157], v158 offset:2048
	ds_read_b128 v[158:161], v158 offset:3072
	ds_read_b128 v[162:165], v197 offset:32768
	ds_read_b128 v[166:169], v197 offset:33792
	ds_read_b128 v[170:173], v197 offset:34816
	ds_read_b128 v[174:177], v197 offset:35840
	ds_read_b128 v[178:181], v197 offset:36864
	ds_read_b128 v[182:185], v197 offset:37888
	ds_read_b128 v[186:189], v197 offset:38912
	ds_read_b128 v[220:223], v197 offset:39936
	s_waitcnt vmcnt(8)
	s_waitcnt lgkmcnt(0)
	s_barrier
	s_setprio 1
	s_waitcnt lgkmcnt(0)
	v_mfma_f32_16x16x32_bf16 v[126:129], v[130:133], v[162:165], v[126:129]
	v_mfma_f32_16x16x32_bf16 v[126:129], v[134:137], v[166:169], v[126:129]
	v_mfma_f32_16x16x32_bf16 v[110:113], v[134:137], v[174:177], v[110:113]
	v_mfma_f32_16x16x32_bf16 v[110:113], v[130:133], v[170:173], v[110:113]
	v_mfma_f32_16x16x32_bf16 v[98:101], v[130:133], v[178:181], v[98:101]
	v_mfma_f32_16x16x32_bf16 v[98:101], v[134:137], v[182:185], v[98:101]
	v_mfma_f32_16x16x32_bf16 v[82:85], v[134:137], v[220:223], v[82:85]
	v_mfma_f32_16x16x32_bf16 v[82:85], v[130:133], v[186:189], v[82:85]
	v_mfma_f32_16x16x32_bf16 v[74:77], v[138:141], v[186:189], v[74:77]
	v_mfma_f32_16x16x32_bf16 v[74:77], v[142:145], v[220:223], v[74:77]
	v_mfma_f32_16x16x32_bf16 v[90:93], v[142:145], v[182:185], v[90:93]
	v_mfma_f32_16x16x32_bf16 v[90:93], v[138:141], v[178:181], v[90:93]
	v_mfma_f32_16x16x32_bf16 v[106:109], v[138:141], v[170:173], v[106:109]
	v_mfma_f32_16x16x32_bf16 v[106:109], v[142:145], v[174:177], v[106:109]
	v_mfma_f32_16x16x32_bf16 v[122:125], v[142:145], v[166:169], v[122:125]
	v_mfma_f32_16x16x32_bf16 v[122:125], v[138:141], v[162:165], v[122:125]
	v_mfma_f32_16x16x32_bf16 v[114:117], v[154:157], v[162:165], v[114:117]
	v_mfma_f32_16x16x32_bf16 v[114:117], v[158:161], v[166:169], v[114:117]
	v_mfma_f32_16x16x32_bf16 v[94:97], v[158:161], v[174:177], v[94:97]
	v_mfma_f32_16x16x32_bf16 v[94:97], v[154:157], v[170:173], v[94:97]
	v_mfma_f32_16x16x32_bf16 v[78:81], v[154:157], v[178:181], v[78:81]
	v_mfma_f32_16x16x32_bf16 v[78:81], v[158:161], v[182:185], v[78:81]
	v_mfma_f32_16x16x32_bf16 v[66:69], v[158:161], v[220:223], v[66:69]
	v_mfma_f32_16x16x32_bf16 v[66:69], v[154:157], v[186:189], v[66:69]
	v_mfma_f32_16x16x32_bf16 v[70:73], v[146:149], v[186:189], v[70:73]
	v_mfma_f32_16x16x32_bf16 v[70:73], v[150:153], v[220:223], v[70:73]
	v_mfma_f32_16x16x32_bf16 v[86:89], v[150:153], v[182:185], v[86:89]
	v_mfma_f32_16x16x32_bf16 v[86:89], v[146:149], v[178:181], v[86:89]
	v_mfma_f32_16x16x32_bf16 v[102:105], v[146:149], v[170:173], v[102:105]
	v_mfma_f32_16x16x32_bf16 v[102:105], v[150:153], v[174:177], v[102:105]
	v_mfma_f32_16x16x32_bf16 v[118:121], v[150:153], v[166:169], v[118:121]
	v_mfma_f32_16x16x32_bf16 v[118:121], v[146:149], v[162:165], v[118:121]
	s_setprio 0
	s_barrier
	s_add_i32 s12, s56, s29
	v_lshl_add_u64 v[224:225], v[224:225], 0, s[34:35]
	s_mov_b32 m0, s12
	global_load_lds_dwordx4 v[224:225], off
	s_add_i32 m0, s12, 0x2000
	s_add_u32 s12, s52, 0x100080
	v_lshl_add_u64 v[224:225], v[226:227], 0, s[34:35]
	s_addc_u32 s13, s53, 0
	s_add_i32 s52, s73, s29
	global_load_lds_dwordx4 v[224:225], off
	v_lshl_add_u64 v[224:225], s[12:13], 0, v[190:191]
	s_mov_b32 m0, s52
	s_nop 0
	global_load_lds_dwordx4 v[224:225], off
	v_lshl_add_u64 v[224:225], s[12:13], 0, v[214:215]
	s_add_i32 m0, s52, 0x2000
	s_nop 0
	global_load_lds_dwordx4 v[224:225], off
	v_lshl_add_u64 v[224:225], v[228:229], 0, s[34:35]
	s_mov_b32 m0, s65
	s_nop 0
	global_load_lds_dwordx4 v[224:225], off
	v_lshl_add_u64 v[224:225], v[230:231], 0, s[34:35]
	s_mov_b32 m0, s66
	s_nop 0
	global_load_lds_dwordx4 v[224:225], off
	ds_read_b128 v[162:165], v197 offset:49152
	ds_read_b128 v[166:169], v197 offset:50176
	ds_read_b128 v[170:173], v197 offset:51200
	ds_read_b128 v[174:177], v197 offset:52224
	ds_read_b128 v[178:181], v197 offset:53248
	ds_read_b128 v[182:185], v197 offset:54272
	ds_read_b128 v[186:189], v197 offset:55296
	ds_read_b128 v[220:223], v197 offset:56320
	s_waitcnt vmcnt(8)
	s_waitcnt lgkmcnt(0)
	s_barrier
	s_setprio 1
	s_waitcnt lgkmcnt(0)
	v_mfma_f32_16x16x32_bf16 v[62:65], v[130:133], v[162:165], v[62:65]
	v_mfma_f32_16x16x32_bf16 v[62:65], v[134:137], v[166:169], v[62:65]
	v_mfma_f32_16x16x32_bf16 v[50:53], v[134:137], v[174:177], v[50:53]
	v_mfma_f32_16x16x32_bf16 v[50:53], v[130:133], v[170:173], v[50:53]
	v_mfma_f32_16x16x32_bf16 v[34:37], v[130:133], v[178:181], v[34:37]
	v_mfma_f32_16x16x32_bf16 v[34:37], v[134:137], v[182:185], v[34:37]
	v_mfma_f32_16x16x32_bf16 v[18:21], v[134:137], v[220:223], v[18:21]
	v_mfma_f32_16x16x32_bf16 v[18:21], v[130:133], v[186:189], v[18:21]
	v_mfma_f32_16x16x32_bf16 v[10:13], v[138:141], v[186:189], v[10:13]
	v_mfma_f32_16x16x32_bf16 v[10:13], v[142:145], v[220:223], v[10:13]
	v_mfma_f32_16x16x32_bf16 v[26:29], v[142:145], v[182:185], v[26:29]
	v_mfma_f32_16x16x32_bf16 v[26:29], v[138:141], v[178:181], v[26:29]
	v_mfma_f32_16x16x32_bf16 v[42:45], v[138:141], v[170:173], v[42:45]
	v_mfma_f32_16x16x32_bf16 v[42:45], v[142:145], v[174:177], v[42:45]
	v_mfma_f32_16x16x32_bf16 v[58:61], v[142:145], v[166:169], v[58:61]
	v_mfma_f32_16x16x32_bf16 v[58:61], v[138:141], v[162:165], v[58:61]
	v_mfma_f32_16x16x32_bf16 v[46:49], v[154:157], v[162:165], v[46:49]
	v_mfma_f32_16x16x32_bf16 v[46:49], v[158:161], v[166:169], v[46:49]
	v_mfma_f32_16x16x32_bf16 v[30:33], v[158:161], v[174:177], v[30:33]
	v_mfma_f32_16x16x32_bf16 v[30:33], v[154:157], v[170:173], v[30:33]
	v_mfma_f32_16x16x32_bf16 v[14:17], v[154:157], v[178:181], v[14:17]
	v_mfma_f32_16x16x32_bf16 v[14:17], v[158:161], v[182:185], v[14:17]
	v_mfma_f32_16x16x32_bf16 v[2:5], v[158:161], v[220:223], v[2:5]
	v_mfma_f32_16x16x32_bf16 v[2:5], v[154:157], v[186:189], v[2:5]
	v_mfma_f32_16x16x32_bf16 v[6:9], v[146:149], v[186:189], v[6:9]
	v_mfma_f32_16x16x32_bf16 v[6:9], v[150:153], v[220:223], v[6:9]
	v_mfma_f32_16x16x32_bf16 v[22:25], v[150:153], v[182:185], v[22:25]
	v_mfma_f32_16x16x32_bf16 v[22:25], v[146:149], v[178:181], v[22:25]
	v_mfma_f32_16x16x32_bf16 v[38:41], v[146:149], v[170:173], v[38:41]
	v_mfma_f32_16x16x32_bf16 v[38:41], v[150:153], v[174:177], v[38:41]
	v_mfma_f32_16x16x32_bf16 v[54:57], v[150:153], v[166:169], v[54:57]
	v_mfma_f32_16x16x32_bf16 v[54:57], v[146:149], v[162:165], v[54:57]
	s_setprio 0
	s_barrier
	s_add_i32 s72, s72, 2
	s_add_u32 s50, s50, 0x100
	s_addc_u32 s51, s51, 0
	s_add_u32 s71, s71, 0x100
	s_addc_u32 s61, s61, 0
	s_cmp_gt_u32 s72, 61
	s_cbranch_scc0 .LBB0_777
	s_and_b64 vcc, exec, s[30:31]
	s_cbranch_vccz .LBB0_780
	s_barrier

.LBB0_902:
	s_add_u32 s12, s22, 0xfff00080
	s_addc_u32 s13, s23, -1
	s_add_i32 s56, 0, 0x10000
	s_cmp_eq_u32 s47, 60
	s_cselect_b32 s53, s5, s13
	s_cselect_b32 s52, s10, s12
	s_cselect_b32 s31, s25, s45
	s_cselect_b32 s30, s29, s33
	s_add_i32 s61, 0, 0x14000
	v_lshl_add_u64 v[188:189], s[22:23], 0, v[136:137]
	s_add_i32 m0, s63, 0xc000
	global_load_lds_dwordx4 v[188:189], off
	v_lshl_add_u64 v[188:189], s[22:23], 0, v[138:139]
	s_add_i32 m0, s63, 0xe000
	s_nop 0
	global_load_lds_dwordx4 v[188:189], off
	v_add_u32_e32 v147, s56, v144
	ds_read_b128 v[140:143], v147
	ds_read_b128 v[148:151], v147 offset:1024
	ds_read_b128 v[152:155], v147 offset:2048
	ds_read_b128 v[156:159], v147 offset:3072
	v_add_u32_e32 v147, s61, v144
	ds_read_b128 v[160:163], v147
	ds_read_b128 v[164:167], v147 offset:1024
	ds_read_b128 v[168:171], v147 offset:2048
	ds_read_b128 v[172:175], v147 offset:3072
	ds_read_b128 v[176:179], v146
	ds_read_b128 v[180:183], v146 offset:1024
	ds_read_b128 v[184:187], v146 offset:2048
	ds_read_b128 v[210:213], v146 offset:3072
	ds_read_b128 v[214:217], v146 offset:4096
	ds_read_b128 v[218:221], v146 offset:5120
	ds_read_b128 v[222:225], v146 offset:6144
	ds_read_b128 v[226:229], v146 offset:7168
	s_waitcnt vmcnt(8)
	s_waitcnt lgkmcnt(0)
	s_barrier
	s_setprio 1
	s_waitcnt lgkmcnt(0)
	v_mfma_f32_16x16x32_bf16 v[126:129], v[140:143], v[176:179], v[126:129]
	v_mfma_f32_16x16x32_bf16 v[126:129], v[148:151], v[180:183], v[126:129]
	v_mfma_f32_16x16x32_bf16 v[110:113], v[148:151], v[210:213], v[110:113]
	v_mfma_f32_16x16x32_bf16 v[110:113], v[140:143], v[184:187], v[110:113]
	v_mfma_f32_16x16x32_bf16 v[94:97], v[140:143], v[214:217], v[94:97]
	v_mfma_f32_16x16x32_bf16 v[94:97], v[148:151], v[218:221], v[94:97]
	v_mfma_f32_16x16x32_bf16 v[78:81], v[148:151], v[226:229], v[78:81]
	v_mfma_f32_16x16x32_bf16 v[78:81], v[140:143], v[222:225], v[78:81]
	v_mfma_f32_16x16x32_bf16 v[70:73], v[152:155], v[222:225], v[70:73]
	v_mfma_f32_16x16x32_bf16 v[70:73], v[156:159], v[226:229], v[70:73]
	v_mfma_f32_16x16x32_bf16 v[86:89], v[156:159], v[218:221], v[86:89]
	v_mfma_f32_16x16x32_bf16 v[86:89], v[152:155], v[214:217], v[86:89]
	v_mfma_f32_16x16x32_bf16 v[102:105], v[152:155], v[184:187], v[102:105]
	v_mfma_f32_16x16x32_bf16 v[102:105], v[156:159], v[210:213], v[102:105]
	v_mfma_f32_16x16x32_bf16 v[118:121], v[156:159], v[180:183], v[118:121]
	v_mfma_f32_16x16x32_bf16 v[118:121], v[152:155], v[176:179], v[118:121]
	v_mfma_f32_16x16x32_bf16 v[114:117], v[168:171], v[176:179], v[114:117]
	v_mfma_f32_16x16x32_bf16 v[114:117], v[172:175], v[180:183], v[114:117]
	v_mfma_f32_16x16x32_bf16 v[98:101], v[172:175], v[210:213], v[98:101]
	v_mfma_f32_16x16x32_bf16 v[98:101], v[168:171], v[184:187], v[98:101]
	v_mfma_f32_16x16x32_bf16 v[82:85], v[168:171], v[214:217], v[82:85]
	v_mfma_f32_16x16x32_bf16 v[82:85], v[172:175], v[218:221], v[82:85]
	v_mfma_f32_16x16x32_bf16 v[66:69], v[172:175], v[226:229], v[66:69]
	v_mfma_f32_16x16x32_bf16 v[66:69], v[168:171], v[222:225], v[66:69]
	v_mfma_f32_16x16x32_bf16 v[74:77], v[160:163], v[222:225], v[74:77]
	v_mfma_f32_16x16x32_bf16 v[74:77], v[164:167], v[226:229], v[74:77]
	v_mfma_f32_16x16x32_bf16 v[90:93], v[164:167], v[218:221], v[90:93]
	v_mfma_f32_16x16x32_bf16 v[90:93], v[160:163], v[214:217], v[90:93]
	v_mfma_f32_16x16x32_bf16 v[106:109], v[160:163], v[184:187], v[106:109]
	v_mfma_f32_16x16x32_bf16 v[106:109], v[164:167], v[210:213], v[106:109]
	v_mfma_f32_16x16x32_bf16 v[122:125], v[164:167], v[180:183], v[122:125]
	v_mfma_f32_16x16x32_bf16 v[122:125], v[160:163], v[176:179], v[122:125]
	s_setprio 0
	s_barrier
	s_add_i32 s12, s56, s60
	v_lshl_add_u64 v[188:189], s[30:31], 0, v[190:191]
	s_mov_b32 m0, s12
	global_load_lds_dwordx4 v[188:189], off
	s_add_i32 m0, s12, 0x2000
	s_add_u32 s12, s30, 0x100000
	v_lshl_add_u64 v[230:231], s[30:31], 0, v[130:131]
	s_addc_u32 s13, s31, 0
	s_add_i32 s56, s61, s60
	global_load_lds_dwordx4 v[230:231], off
	v_lshl_add_u64 v[232:233], s[12:13], 0, v[190:191]
	s_mov_b32 m0, s56
	v_lshl_add_u64 v[234:235], s[52:53], 0, v[132:133]
	global_load_lds_dwordx4 v[232:233], off
	v_lshl_add_u64 v[232:233], s[12:13], 0, v[130:131]
	s_add_i32 m0, s56, 0x2000
	s_nop 0
	global_load_lds_dwordx4 v[232:233], off
	v_lshl_add_u64 v[232:233], s[52:53], 0, v[134:135]
	s_mov_b32 m0, s63
	s_nop 0
	global_load_lds_dwordx4 v[232:233], off
	s_mov_b32 m0, s64
	s_nop 0
	global_load_lds_dwordx4 v[234:235], off
	ds_read_b128 v[176:179], v146 offset:16384
	ds_read_b128 v[180:183], v146 offset:17408
	ds_read_b128 v[184:187], v146 offset:18432
	ds_read_b128 v[210:213], v146 offset:19456
	ds_read_b128 v[214:217], v146 offset:20480
	ds_read_b128 v[218:221], v146 offset:21504
	ds_read_b128 v[222:225], v146 offset:22528
	ds_read_b128 v[226:229], v146 offset:23552
	s_waitcnt vmcnt(8)
	s_waitcnt lgkmcnt(0)
	s_barrier
	s_setprio 1
	s_waitcnt lgkmcnt(0)
	v_mfma_f32_16x16x32_bf16 v[62:65], v[140:143], v[176:179], v[62:65]
	v_mfma_f32_16x16x32_bf16 v[62:65], v[148:151], v[180:183], v[62:65]
	v_mfma_f32_16x16x32_bf16 v[46:49], v[148:151], v[210:213], v[46:49]
	v_mfma_f32_16x16x32_bf16 v[46:49], v[140:143], v[184:187], v[46:49]
	v_mfma_f32_16x16x32_bf16 v[30:33], v[140:143], v[214:217], v[30:33]
	v_mfma_f32_16x16x32_bf16 v[30:33], v[148:151], v[218:221], v[30:33]
	v_mfma_f32_16x16x32_bf16 v[14:17], v[148:151], v[226:229], v[14:17]
	v_mfma_f32_16x16x32_bf16 v[14:17], v[140:143], v[222:225], v[14:17]
	v_mfma_f32_16x16x32_bf16 v[6:9], v[152:155], v[222:225], v[6:9]
	v_mfma_f32_16x16x32_bf16 v[6:9], v[156:159], v[226:229], v[6:9]
	v_mfma_f32_16x16x32_bf16 v[22:25], v[156:159], v[218:221], v[22:25]
	v_mfma_f32_16x16x32_bf16 v[22:25], v[152:155], v[214:217], v[22:25]
	v_mfma_f32_16x16x32_bf16 v[38:41], v[152:155], v[184:187], v[38:41]
	v_mfma_f32_16x16x32_bf16 v[38:41], v[156:159], v[210:213], v[38:41]
	v_mfma_f32_16x16x32_bf16 v[54:57], v[156:159], v[180:183], v[54:57]
	v_mfma_f32_16x16x32_bf16 v[54:57], v[152:155], v[176:179], v[54:57]
	v_mfma_f32_16x16x32_bf16 v[50:53], v[168:171], v[176:179], v[50:53]
	v_mfma_f32_16x16x32_bf16 v[50:53], v[172:175], v[180:183], v[50:53]
	v_mfma_f32_16x16x32_bf16 v[34:37], v[172:175], v[210:213], v[34:37]
	v_mfma_f32_16x16x32_bf16 v[34:37], v[168:171], v[184:187], v[34:37]
	v_mfma_f32_16x16x32_bf16 v[18:21], v[168:171], v[214:217], v[18:21]
	v_mfma_f32_16x16x32_bf16 v[18:21], v[172:175], v[218:221], v[18:21]
	v_mfma_f32_16x16x32_bf16 v[2:5], v[172:175], v[226:229], v[2:5]
	v_mfma_f32_16x16x32_bf16 v[2:5], v[168:171], v[222:225], v[2:5]
	v_mfma_f32_16x16x32_bf16 v[10:13], v[160:163], v[222:225], v[10:13]
	v_mfma_f32_16x16x32_bf16 v[10:13], v[164:167], v[226:229], v[10:13]
	v_mfma_f32_16x16x32_bf16 v[26:29], v[164:167], v[218:221], v[26:29]
	v_mfma_f32_16x16x32_bf16 v[26:29], v[160:163], v[214:217], v[26:29]
	v_mfma_f32_16x16x32_bf16 v[42:45], v[160:163], v[184:187], v[42:45]
	v_mfma_f32_16x16x32_bf16 v[42:45], v[164:167], v[210:213], v[42:45]
	v_mfma_f32_16x16x32_bf16 v[58:61], v[164:167], v[180:183], v[58:61]
	v_mfma_f32_16x16x32_bf16 v[58:61], v[160:163], v[176:179], v[58:61]
	s_setprio 0
	s_barrier
	s_add_i32 s56, 0, 0x18000
	s_add_i32 s61, 0, 0x1c000
	s_add_u32 s12, s52, 0x100000
	s_addc_u32 s13, s53, 0
	s_mov_b32 m0, s65
	v_lshl_add_u64 v[244:245], s[12:13], 0, v[134:135]
	global_load_lds_dwordx4 v[244:245], off
	v_lshl_add_u64 v[244:245], s[12:13], 0, v[132:133]
	s_mov_b32 m0, s66
	s_nop 0
	global_load_lds_dwordx4 v[244:245], off
	v_add_u32_e32 v147, s56, v144
	ds_read_b128 v[140:143], v147
	ds_read_b128 v[148:151], v147 offset:1024
	ds_read_b128 v[152:155], v147 offset:2048
	ds_read_b128 v[156:159], v147 offset:3072
	v_add_u32_e32 v147, s61, v144
	ds_read_b128 v[160:163], v147
	ds_read_b128 v[164:167], v147 offset:1024
	ds_read_b128 v[168:171], v147 offset:2048
	ds_read_b128 v[172:175], v147 offset:3072
	ds_read_b128 v[176:179], v146 offset:32768
	ds_read_b128 v[180:183], v146 offset:33792
	ds_read_b128 v[184:187], v146 offset:34816
	ds_read_b128 v[210:213], v146 offset:35840
	ds_read_b128 v[214:217], v146 offset:36864
	ds_read_b128 v[218:221], v146 offset:37888
	ds_read_b128 v[222:225], v146 offset:38912
	ds_read_b128 v[226:229], v146 offset:39936
	s_waitcnt vmcnt(8)
	s_waitcnt lgkmcnt(0)
	s_barrier
	s_setprio 1
	s_waitcnt lgkmcnt(0)
	v_mfma_f32_16x16x32_bf16 v[126:129], v[140:143], v[176:179], v[126:129]
	v_mfma_f32_16x16x32_bf16 v[126:129], v[148:151], v[180:183], v[126:129]
	v_mfma_f32_16x16x32_bf16 v[110:113], v[148:151], v[210:213], v[110:113]
	v_mfma_f32_16x16x32_bf16 v[110:113], v[140:143], v[184:187], v[110:113]
	v_mfma_f32_16x16x32_bf16 v[94:97], v[140:143], v[214:217], v[94:97]
	v_mfma_f32_16x16x32_bf16 v[94:97], v[148:151], v[218:221], v[94:97]
	v_mfma_f32_16x16x32_bf16 v[78:81], v[148:151], v[226:229], v[78:81]
	v_mfma_f32_16x16x32_bf16 v[78:81], v[140:143], v[222:225], v[78:81]
	v_mfma_f32_16x16x32_bf16 v[70:73], v[152:155], v[222:225], v[70:73]
	v_mfma_f32_16x16x32_bf16 v[70:73], v[156:159], v[226:229], v[70:73]
	v_mfma_f32_16x16x32_bf16 v[86:89], v[156:159], v[218:221], v[86:89]
	v_mfma_f32_16x16x32_bf16 v[86:89], v[152:155], v[214:217], v[86:89]
	v_mfma_f32_16x16x32_bf16 v[102:105], v[152:155], v[184:187], v[102:105]
	v_mfma_f32_16x16x32_bf16 v[102:105], v[156:159], v[210:213], v[102:105]
	v_mfma_f32_16x16x32_bf16 v[118:121], v[156:159], v[180:183], v[118:121]
	v_mfma_f32_16x16x32_bf16 v[118:121], v[152:155], v[176:179], v[118:121]
	v_mfma_f32_16x16x32_bf16 v[114:117], v[168:171], v[176:179], v[114:117]
	v_mfma_f32_16x16x32_bf16 v[114:117], v[172:175], v[180:183], v[114:117]
	v_mfma_f32_16x16x32_bf16 v[98:101], v[172:175], v[210:213], v[98:101]
	v_mfma_f32_16x16x32_bf16 v[98:101], v[168:171], v[184:187], v[98:101]
	v_mfma_f32_16x16x32_bf16 v[82:85], v[168:171], v[214:217], v[82:85]
	v_mfma_f32_16x16x32_bf16 v[82:85], v[172:175], v[218:221], v[82:85]
	v_mfma_f32_16x16x32_bf16 v[66:69], v[172:175], v[226:229], v[66:69]
	v_mfma_f32_16x16x32_bf16 v[66:69], v[168:171], v[222:225], v[66:69]
	v_mfma_f32_16x16x32_bf16 v[74:77], v[160:163], v[222:225], v[74:77]
	v_mfma_f32_16x16x32_bf16 v[74:77], v[164:167], v[226:229], v[74:77]
	v_mfma_f32_16x16x32_bf16 v[90:93], v[164:167], v[218:221], v[90:93]
	v_mfma_f32_16x16x32_bf16 v[90:93], v[160:163], v[214:217], v[90:93]
	v_mfma_f32_16x16x32_bf16 v[106:109], v[160:163], v[184:187], v[106:109]
	v_mfma_f32_16x16x32_bf16 v[106:109], v[164:167], v[210:213], v[106:109]
	v_mfma_f32_16x16x32_bf16 v[122:125], v[164:167], v[180:183], v[122:125]
	v_mfma_f32_16x16x32_bf16 v[122:125], v[160:163], v[176:179], v[122:125]
	s_setprio 0
	s_barrier
	s_add_i32 s12, s56, s60
	v_lshl_add_u64 v[188:189], v[188:189], 0, s[34:35]
	s_mov_b32 m0, s12
	global_load_lds_dwordx4 v[188:189], off
	s_add_i32 m0, s12, 0x2000
	s_add_u32 s12, s30, 0x100080
	v_lshl_add_u64 v[188:189], v[230:231], 0, s[34:35]
	s_addc_u32 s13, s31, 0
	s_add_i32 s30, s61, s60
	global_load_lds_dwordx4 v[188:189], off
	v_lshl_add_u64 v[188:189], s[12:13], 0, v[190:191]
	s_mov_b32 m0, s30
	s_nop 0
	global_load_lds_dwordx4 v[188:189], off
	v_lshl_add_u64 v[188:189], s[12:13], 0, v[130:131]
	s_add_i32 m0, s30, 0x2000
	s_nop 0
	global_load_lds_dwordx4 v[188:189], off
	v_lshl_add_u64 v[188:189], v[232:233], 0, s[34:35]
	s_mov_b32 m0, s68
	s_nop 0
	global_load_lds_dwordx4 v[188:189], off
	v_lshl_add_u64 v[188:189], v[234:235], 0, s[34:35]
	s_mov_b32 m0, s69
	s_nop 0
	global_load_lds_dwordx4 v[188:189], off
	ds_read_b128 v[176:179], v146 offset:49152
	ds_read_b128 v[180:183], v146 offset:50176
	ds_read_b128 v[184:187], v146 offset:51200
	ds_read_b128 v[210:213], v146 offset:52224
	ds_read_b128 v[214:217], v146 offset:53248
	ds_read_b128 v[218:221], v146 offset:54272
	ds_read_b128 v[222:225], v146 offset:55296
	ds_read_b128 v[226:229], v146 offset:56320
	s_waitcnt vmcnt(8)
	s_waitcnt lgkmcnt(0)
	s_barrier
	s_setprio 1
	s_waitcnt lgkmcnt(0)
	v_mfma_f32_16x16x32_bf16 v[62:65], v[140:143], v[176:179], v[62:65]
	v_mfma_f32_16x16x32_bf16 v[62:65], v[148:151], v[180:183], v[62:65]
	v_mfma_f32_16x16x32_bf16 v[46:49], v[148:151], v[210:213], v[46:49]
	v_mfma_f32_16x16x32_bf16 v[46:49], v[140:143], v[184:187], v[46:49]
	v_mfma_f32_16x16x32_bf16 v[30:33], v[140:143], v[214:217], v[30:33]
	v_mfma_f32_16x16x32_bf16 v[30:33], v[148:151], v[218:221], v[30:33]
	v_mfma_f32_16x16x32_bf16 v[14:17], v[148:151], v[226:229], v[14:17]
	v_mfma_f32_16x16x32_bf16 v[14:17], v[140:143], v[222:225], v[14:17]
	v_mfma_f32_16x16x32_bf16 v[6:9], v[152:155], v[222:225], v[6:9]
	v_mfma_f32_16x16x32_bf16 v[6:9], v[156:159], v[226:229], v[6:9]
	v_mfma_f32_16x16x32_bf16 v[22:25], v[156:159], v[218:221], v[22:25]
	v_mfma_f32_16x16x32_bf16 v[22:25], v[152:155], v[214:217], v[22:25]
	v_mfma_f32_16x16x32_bf16 v[38:41], v[152:155], v[184:187], v[38:41]
	v_mfma_f32_16x16x32_bf16 v[38:41], v[156:159], v[210:213], v[38:41]
	v_mfma_f32_16x16x32_bf16 v[54:57], v[156:159], v[180:183], v[54:57]
	v_mfma_f32_16x16x32_bf16 v[54:57], v[152:155], v[176:179], v[54:57]
	v_mfma_f32_16x16x32_bf16 v[50:53], v[168:171], v[176:179], v[50:53]
	v_mfma_f32_16x16x32_bf16 v[50:53], v[172:175], v[180:183], v[50:53]
	v_mfma_f32_16x16x32_bf16 v[34:37], v[172:175], v[210:213], v[34:37]
	v_mfma_f32_16x16x32_bf16 v[34:37], v[168:171], v[184:187], v[34:37]
	v_mfma_f32_16x16x32_bf16 v[18:21], v[168:171], v[214:217], v[18:21]
	v_mfma_f32_16x16x32_bf16 v[18:21], v[172:175], v[218:221], v[18:21]
	v_mfma_f32_16x16x32_bf16 v[2:5], v[172:175], v[226:229], v[2:5]
	v_mfma_f32_16x16x32_bf16 v[2:5], v[168:171], v[222:225], v[2:5]
	v_mfma_f32_16x16x32_bf16 v[10:13], v[160:163], v[222:225], v[10:13]
	v_mfma_f32_16x16x32_bf16 v[10:13], v[164:167], v[226:229], v[10:13]
	v_mfma_f32_16x16x32_bf16 v[26:29], v[164:167], v[218:221], v[26:29]
	v_mfma_f32_16x16x32_bf16 v[26:29], v[160:163], v[214:217], v[26:29]
	v_mfma_f32_16x16x32_bf16 v[42:45], v[160:163], v[184:187], v[42:45]
	v_mfma_f32_16x16x32_bf16 v[42:45], v[164:167], v[210:213], v[42:45]
	v_mfma_f32_16x16x32_bf16 v[58:61], v[164:167], v[180:183], v[58:61]
	v_mfma_f32_16x16x32_bf16 v[58:61], v[160:163], v[176:179], v[58:61]
	s_setprio 0
	s_barrier
	s_add_i32 s47, s47, 2
	s_add_u32 s22, s22, 0x100
	s_addc_u32 s23, s23, 0
	s_add_u32 s33, s33, 0x100
	s_addc_u32 s45, s45, 0
	s_cmp_gt_u32 s47, 61
	s_cbranch_scc0 .LBB0_902
	s_and_b64 vcc, exec, s[42:43]
	s_cbranch_vccz .LBB0_905
	s_barrier

.LBB0_983:
	s_add_u32 s46, s44, 0x100
	s_addc_u32 s47, s45, 0
	s_add_i32 s12, 0, 0x10000
	s_cmpk_eq_i32 s70, 0xa8
	s_cselect_b32 s51, s41, s47
	s_cselect_b32 s50, s40, s46
	s_cselect_b32 s49, s43, s69
	s_cselect_b32 s48, s42, s61
	s_add_i32 s56, 0, 0x14000
	v_lshl_add_u64 v[224:225], s[44:45], 0, v[216:217]
	s_add_i32 m0, s33, 0xc000
	global_load_lds_dwordx4 v[224:225], off
	v_lshl_add_u64 v[224:225], s[44:45], 0, v[218:219]
	s_add_i32 m0, s33, 0xe000
	s_nop 0
	global_load_lds_dwordx4 v[224:225], off
	v_add_u32_e32 v142, s12, v193
	v_add_u32_e32 v158, s56, v193
	ds_read_b128 v[130:133], v142
	ds_read_b128 v[134:137], v142 offset:1024
	ds_read_b128 v[138:141], v142 offset:2048
	ds_read_b128 v[142:145], v142 offset:3072
	ds_read_b128 v[146:149], v158
	ds_read_b128 v[150:153], v158 offset:1024
	ds_read_b128 v[154:157], v158 offset:2048
	ds_read_b128 v[158:161], v158 offset:3072
	ds_read_b128 v[162:165], v197
	ds_read_b128 v[166:169], v197 offset:1024
	ds_read_b128 v[170:173], v197 offset:2048
	ds_read_b128 v[174:177], v197 offset:3072
	ds_read_b128 v[178:181], v197 offset:4096
	ds_read_b128 v[182:185], v197 offset:5120
	ds_read_b128 v[186:189], v197 offset:6144
	ds_read_b128 v[220:223], v197 offset:7168
	s_waitcnt vmcnt(8)
	s_waitcnt lgkmcnt(0)
	s_barrier
	s_setprio 1
	s_waitcnt lgkmcnt(0)
	v_mfma_f32_16x16x32_bf16 v[126:129], v[130:133], v[162:165], v[126:129]
	v_mfma_f32_16x16x32_bf16 v[126:129], v[134:137], v[166:169], v[126:129]
	v_mfma_f32_16x16x32_bf16 v[110:113], v[134:137], v[174:177], v[110:113]
	v_mfma_f32_16x16x32_bf16 v[110:113], v[130:133], v[170:173], v[110:113]
	v_mfma_f32_16x16x32_bf16 v[98:101], v[130:133], v[178:181], v[98:101]
	v_mfma_f32_16x16x32_bf16 v[98:101], v[134:137], v[182:185], v[98:101]
	v_mfma_f32_16x16x32_bf16 v[82:85], v[134:137], v[220:223], v[82:85]
	v_mfma_f32_16x16x32_bf16 v[82:85], v[130:133], v[186:189], v[82:85]
	v_mfma_f32_16x16x32_bf16 v[74:77], v[138:141], v[186:189], v[74:77]
	v_mfma_f32_16x16x32_bf16 v[74:77], v[142:145], v[220:223], v[74:77]
	v_mfma_f32_16x16x32_bf16 v[90:93], v[142:145], v[182:185], v[90:93]
	v_mfma_f32_16x16x32_bf16 v[90:93], v[138:141], v[178:181], v[90:93]
	v_mfma_f32_16x16x32_bf16 v[106:109], v[138:141], v[170:173], v[106:109]
	v_mfma_f32_16x16x32_bf16 v[106:109], v[142:145], v[174:177], v[106:109]
	v_mfma_f32_16x16x32_bf16 v[122:125], v[142:145], v[166:169], v[122:125]
	v_mfma_f32_16x16x32_bf16 v[122:125], v[138:141], v[162:165], v[122:125]
	v_mfma_f32_16x16x32_bf16 v[114:117], v[154:157], v[162:165], v[114:117]
	v_mfma_f32_16x16x32_bf16 v[114:117], v[158:161], v[166:169], v[114:117]
	v_mfma_f32_16x16x32_bf16 v[94:97], v[158:161], v[174:177], v[94:97]
	v_mfma_f32_16x16x32_bf16 v[94:97], v[154:157], v[170:173], v[94:97]
	v_mfma_f32_16x16x32_bf16 v[78:81], v[154:157], v[178:181], v[78:81]
	v_mfma_f32_16x16x32_bf16 v[78:81], v[158:161], v[182:185], v[78:81]
	v_mfma_f32_16x16x32_bf16 v[66:69], v[158:161], v[220:223], v[66:69]
	v_mfma_f32_16x16x32_bf16 v[66:69], v[154:157], v[186:189], v[66:69]
	v_mfma_f32_16x16x32_bf16 v[70:73], v[146:149], v[186:189], v[70:73]
	v_mfma_f32_16x16x32_bf16 v[70:73], v[150:153], v[220:223], v[70:73]
	v_mfma_f32_16x16x32_bf16 v[86:89], v[150:153], v[182:185], v[86:89]
	v_mfma_f32_16x16x32_bf16 v[86:89], v[146:149], v[178:181], v[86:89]
	v_mfma_f32_16x16x32_bf16 v[102:105], v[146:149], v[170:173], v[102:105]
	v_mfma_f32_16x16x32_bf16 v[102:105], v[150:153], v[174:177], v[102:105]
	v_mfma_f32_16x16x32_bf16 v[118:121], v[150:153], v[166:169], v[118:121]
	v_mfma_f32_16x16x32_bf16 v[118:121], v[146:149], v[162:165], v[118:121]
	s_setprio 0
	s_barrier
	s_add_i32 s12, s12, s29
	v_lshl_add_u64 v[224:225], s[48:49], 0, v[190:191]
	s_mov_b32 m0, s12
	global_load_lds_dwordx4 v[224:225], off
	s_add_i32 m0, s12, 0x2000
	s_add_u32 s12, s48, 0x2b0000
	v_lshl_add_u64 v[226:227], s[48:49], 0, v[214:215]
	s_addc_u32 s13, s49, 0
	s_add_i32 s44, s56, s29
	global_load_lds_dwordx4 v[226:227], off
	v_lshl_add_u64 v[228:229], s[12:13], 0, v[190:191]
	s_mov_b32 m0, s44
	v_lshl_add_u64 v[230:231], s[50:51], 0, v[212:213]
	global_load_lds_dwordx4 v[228:229], off
	v_lshl_add_u64 v[228:229], s[12:13], 0, v[214:215]
	s_add_i32 m0, s44, 0x2000
	s_nop 0
	global_load_lds_dwordx4 v[228:229], off
	v_lshl_add_u64 v[228:229], s[50:51], 0, v[210:211]
	s_mov_b32 m0, s33
	s_nop 0
	global_load_lds_dwordx4 v[228:229], off
	s_mov_b32 m0, s57
	s_nop 0
	global_load_lds_dwordx4 v[230:231], off
	ds_read_b128 v[162:165], v197 offset:16384
	ds_read_b128 v[166:169], v197 offset:17408
	ds_read_b128 v[170:173], v197 offset:18432
	ds_read_b128 v[174:177], v197 offset:19456
	ds_read_b128 v[178:181], v197 offset:20480
	ds_read_b128 v[182:185], v197 offset:21504
	ds_read_b128 v[186:189], v197 offset:22528
	ds_read_b128 v[220:223], v197 offset:23552
	s_waitcnt vmcnt(8)
	s_waitcnt lgkmcnt(0)
	s_barrier
	s_setprio 1
	s_waitcnt lgkmcnt(0)
	v_mfma_f32_16x16x32_bf16 v[62:65], v[130:133], v[162:165], v[62:65]
	v_mfma_f32_16x16x32_bf16 v[62:65], v[134:137], v[166:169], v[62:65]
	v_mfma_f32_16x16x32_bf16 v[50:53], v[134:137], v[174:177], v[50:53]
	v_mfma_f32_16x16x32_bf16 v[50:53], v[130:133], v[170:173], v[50:53]
	v_mfma_f32_16x16x32_bf16 v[34:37], v[130:133], v[178:181], v[34:37]
	v_mfma_f32_16x16x32_bf16 v[34:37], v[134:137], v[182:185], v[34:37]
	v_mfma_f32_16x16x32_bf16 v[18:21], v[134:137], v[220:223], v[18:21]
	v_mfma_f32_16x16x32_bf16 v[18:21], v[130:133], v[186:189], v[18:21]
	v_mfma_f32_16x16x32_bf16 v[10:13], v[138:141], v[186:189], v[10:13]
	v_mfma_f32_16x16x32_bf16 v[10:13], v[142:145], v[220:223], v[10:13]
	v_mfma_f32_16x16x32_bf16 v[26:29], v[142:145], v[182:185], v[26:29]
	v_mfma_f32_16x16x32_bf16 v[26:29], v[138:141], v[178:181], v[26:29]
	v_mfma_f32_16x16x32_bf16 v[42:45], v[138:141], v[170:173], v[42:45]
	v_mfma_f32_16x16x32_bf16 v[42:45], v[142:145], v[174:177], v[42:45]
	v_mfma_f32_16x16x32_bf16 v[58:61], v[142:145], v[166:169], v[58:61]
	v_mfma_f32_16x16x32_bf16 v[58:61], v[138:141], v[162:165], v[58:61]
	v_mfma_f32_16x16x32_bf16 v[46:49], v[154:157], v[162:165], v[46:49]
	v_mfma_f32_16x16x32_bf16 v[46:49], v[158:161], v[166:169], v[46:49]
	v_mfma_f32_16x16x32_bf16 v[30:33], v[158:161], v[174:177], v[30:33]
	v_mfma_f32_16x16x32_bf16 v[30:33], v[154:157], v[170:173], v[30:33]
	v_mfma_f32_16x16x32_bf16 v[14:17], v[154:157], v[178:181], v[14:17]
	v_mfma_f32_16x16x32_bf16 v[14:17], v[158:161], v[182:185], v[14:17]
	v_mfma_f32_16x16x32_bf16 v[2:5], v[158:161], v[220:223], v[2:5]
	v_mfma_f32_16x16x32_bf16 v[2:5], v[154:157], v[186:189], v[2:5]
	v_mfma_f32_16x16x32_bf16 v[6:9], v[146:149], v[186:189], v[6:9]
	v_mfma_f32_16x16x32_bf16 v[6:9], v[150:153], v[220:223], v[6:9]
	v_mfma_f32_16x16x32_bf16 v[22:25], v[150:153], v[182:185], v[22:25]
	v_mfma_f32_16x16x32_bf16 v[22:25], v[146:149], v[178:181], v[22:25]
	v_mfma_f32_16x16x32_bf16 v[38:41], v[146:149], v[170:173], v[38:41]
	v_mfma_f32_16x16x32_bf16 v[38:41], v[150:153], v[174:177], v[38:41]
	v_mfma_f32_16x16x32_bf16 v[54:57], v[150:153], v[166:169], v[54:57]
	v_mfma_f32_16x16x32_bf16 v[54:57], v[146:149], v[162:165], v[54:57]
	s_setprio 0
	s_barrier
	s_add_i32 s44, 0, 0x18000
	s_add_i32 s45, 0, 0x1c000
	s_add_u32 s12, s50, 0x2b0000
	s_addc_u32 s13, s51, 0
	s_mov_b32 m0, s58
	v_lshl_add_u64 v[232:233], s[12:13], 0, v[210:211]
	global_load_lds_dwordx4 v[232:233], off
	v_lshl_add_u64 v[232:233], s[12:13], 0, v[212:213]
	s_mov_b32 m0, s59
	s_nop 0
	global_load_lds_dwordx4 v[232:233], off
	v_add_u32_e32 v142, s44, v193
	v_add_u32_e32 v158, s45, v193
	ds_read_b128 v[130:133], v142
	ds_read_b128 v[134:137], v142 offset:1024
	ds_read_b128 v[138:141], v142 offset:2048
	ds_read_b128 v[142:145], v142 offset:3072
	ds_read_b128 v[146:149], v158
	ds_read_b128 v[150:153], v158 offset:1024
	ds_read_b128 v[154:157], v158 offset:2048
	ds_read_b128 v[158:161], v158 offset:3072
	ds_read_b128 v[162:165], v197 offset:32768
	ds_read_b128 v[166:169], v197 offset:33792
	ds_read_b128 v[170:173], v197 offset:34816
	ds_read_b128 v[174:177], v197 offset:35840
	ds_read_b128 v[178:181], v197 offset:36864
	ds_read_b128 v[182:185], v197 offset:37888
	ds_read_b128 v[186:189], v197 offset:38912
	ds_read_b128 v[220:223], v197 offset:39936
	s_waitcnt vmcnt(8)
	s_waitcnt lgkmcnt(0)
	s_barrier
	s_setprio 1
	s_waitcnt lgkmcnt(0)
	v_mfma_f32_16x16x32_bf16 v[126:129], v[130:133], v[162:165], v[126:129]
	v_mfma_f32_16x16x32_bf16 v[126:129], v[134:137], v[166:169], v[126:129]
	v_mfma_f32_16x16x32_bf16 v[110:113], v[134:137], v[174:177], v[110:113]
	v_mfma_f32_16x16x32_bf16 v[110:113], v[130:133], v[170:173], v[110:113]
	v_mfma_f32_16x16x32_bf16 v[98:101], v[130:133], v[178:181], v[98:101]
	v_mfma_f32_16x16x32_bf16 v[98:101], v[134:137], v[182:185], v[98:101]
	v_mfma_f32_16x16x32_bf16 v[82:85], v[134:137], v[220:223], v[82:85]
	v_mfma_f32_16x16x32_bf16 v[82:85], v[130:133], v[186:189], v[82:85]
	v_mfma_f32_16x16x32_bf16 v[74:77], v[138:141], v[186:189], v[74:77]
	v_mfma_f32_16x16x32_bf16 v[74:77], v[142:145], v[220:223], v[74:77]
	v_mfma_f32_16x16x32_bf16 v[90:93], v[142:145], v[182:185], v[90:93]
	v_mfma_f32_16x16x32_bf16 v[90:93], v[138:141], v[178:181], v[90:93]
	v_mfma_f32_16x16x32_bf16 v[106:109], v[138:141], v[170:173], v[106:109]
	v_mfma_f32_16x16x32_bf16 v[106:109], v[142:145], v[174:177], v[106:109]
	v_mfma_f32_16x16x32_bf16 v[122:125], v[142:145], v[166:169], v[122:125]
	v_mfma_f32_16x16x32_bf16 v[122:125], v[138:141], v[162:165], v[122:125]
	v_mfma_f32_16x16x32_bf16 v[114:117], v[154:157], v[162:165], v[114:117]
	v_mfma_f32_16x16x32_bf16 v[114:117], v[158:161], v[166:169], v[114:117]
	v_mfma_f32_16x16x32_bf16 v[94:97], v[158:161], v[174:177], v[94:97]
	v_mfma_f32_16x16x32_bf16 v[94:97], v[154:157], v[170:173], v[94:97]
	v_mfma_f32_16x16x32_bf16 v[78:81], v[154:157], v[178:181], v[78:81]
	v_mfma_f32_16x16x32_bf16 v[78:81], v[158:161], v[182:185], v[78:81]
	v_mfma_f32_16x16x32_bf16 v[66:69], v[158:161], v[220:223], v[66:69]
	v_mfma_f32_16x16x32_bf16 v[66:69], v[154:157], v[186:189], v[66:69]
	v_mfma_f32_16x16x32_bf16 v[70:73], v[146:149], v[186:189], v[70:73]
	v_mfma_f32_16x16x32_bf16 v[70:73], v[150:153], v[220:223], v[70:73]
	v_mfma_f32_16x16x32_bf16 v[86:89], v[150:153], v[182:185], v[86:89]
	v_mfma_f32_16x16x32_bf16 v[86:89], v[146:149], v[178:181], v[86:89]
	v_mfma_f32_16x16x32_bf16 v[102:105], v[146:149], v[170:173], v[102:105]
	v_mfma_f32_16x16x32_bf16 v[102:105], v[150:153], v[174:177], v[102:105]
	v_mfma_f32_16x16x32_bf16 v[118:121], v[150:153], v[166:169], v[118:121]
	v_mfma_f32_16x16x32_bf16 v[118:121], v[146:149], v[162:165], v[118:121]
	s_setprio 0
	s_barrier
	s_add_i32 s12, s44, s29
	v_lshl_add_u64 v[224:225], v[224:225], 0, s[34:35]
	s_mov_b32 m0, s12
	global_load_lds_dwordx4 v[224:225], off
	s_add_i32 m0, s12, 0x2000
	s_add_u32 s12, s48, 0x2b0080
	v_lshl_add_u64 v[224:225], v[226:227], 0, s[34:35]
	s_addc_u32 s13, s49, 0
	s_add_i32 s44, s45, s29
	global_load_lds_dwordx4 v[224:225], off
	v_lshl_add_u64 v[224:225], s[12:13], 0, v[190:191]
	s_mov_b32 m0, s44
	s_nop 0
	global_load_lds_dwordx4 v[224:225], off
	v_lshl_add_u64 v[224:225], s[12:13], 0, v[214:215]
	s_add_i32 m0, s44, 0x2000
	s_nop 0
	global_load_lds_dwordx4 v[224:225], off
	v_lshl_add_u64 v[224:225], v[228:229], 0, s[34:35]
	s_mov_b32 m0, s60
	s_nop 0
	global_load_lds_dwordx4 v[224:225], off
	v_lshl_add_u64 v[224:225], v[230:231], 0, s[34:35]
	s_mov_b32 m0, s62
	s_nop 0
	global_load_lds_dwordx4 v[224:225], off
	ds_read_b128 v[162:165], v197 offset:49152
	ds_read_b128 v[166:169], v197 offset:50176
	ds_read_b128 v[170:173], v197 offset:51200
	ds_read_b128 v[174:177], v197 offset:52224
	ds_read_b128 v[178:181], v197 offset:53248
	ds_read_b128 v[182:185], v197 offset:54272
	ds_read_b128 v[186:189], v197 offset:55296
	ds_read_b128 v[220:223], v197 offset:56320
	s_waitcnt vmcnt(8)
	s_waitcnt lgkmcnt(0)
	s_barrier
	s_setprio 1
	s_waitcnt lgkmcnt(0)
	v_mfma_f32_16x16x32_bf16 v[62:65], v[130:133], v[162:165], v[62:65]
	v_mfma_f32_16x16x32_bf16 v[62:65], v[134:137], v[166:169], v[62:65]
	v_mfma_f32_16x16x32_bf16 v[50:53], v[134:137], v[174:177], v[50:53]
	v_mfma_f32_16x16x32_bf16 v[50:53], v[130:133], v[170:173], v[50:53]
	v_mfma_f32_16x16x32_bf16 v[34:37], v[130:133], v[178:181], v[34:37]
	v_mfma_f32_16x16x32_bf16 v[34:37], v[134:137], v[182:185], v[34:37]
	v_mfma_f32_16x16x32_bf16 v[18:21], v[134:137], v[220:223], v[18:21]
	v_mfma_f32_16x16x32_bf16 v[18:21], v[130:133], v[186:189], v[18:21]
	v_mfma_f32_16x16x32_bf16 v[10:13], v[138:141], v[186:189], v[10:13]
	v_mfma_f32_16x16x32_bf16 v[10:13], v[142:145], v[220:223], v[10:13]
	v_mfma_f32_16x16x32_bf16 v[26:29], v[142:145], v[182:185], v[26:29]
	v_mfma_f32_16x16x32_bf16 v[26:29], v[138:141], v[178:181], v[26:29]
	v_mfma_f32_16x16x32_bf16 v[42:45], v[138:141], v[170:173], v[42:45]
	v_mfma_f32_16x16x32_bf16 v[42:45], v[142:145], v[174:177], v[42:45]
	v_mfma_f32_16x16x32_bf16 v[58:61], v[142:145], v[166:169], v[58:61]
	v_mfma_f32_16x16x32_bf16 v[58:61], v[138:141], v[162:165], v[58:61]
	v_mfma_f32_16x16x32_bf16 v[46:49], v[154:157], v[162:165], v[46:49]
	v_mfma_f32_16x16x32_bf16 v[46:49], v[158:161], v[166:169], v[46:49]
	v_mfma_f32_16x16x32_bf16 v[30:33], v[158:161], v[174:177], v[30:33]
	v_mfma_f32_16x16x32_bf16 v[30:33], v[154:157], v[170:173], v[30:33]
	v_mfma_f32_16x16x32_bf16 v[14:17], v[154:157], v[178:181], v[14:17]
	v_mfma_f32_16x16x32_bf16 v[14:17], v[158:161], v[182:185], v[14:17]
	v_mfma_f32_16x16x32_bf16 v[2:5], v[158:161], v[220:223], v[2:5]
	v_mfma_f32_16x16x32_bf16 v[2:5], v[154:157], v[186:189], v[2:5]
	v_mfma_f32_16x16x32_bf16 v[6:9], v[146:149], v[186:189], v[6:9]
	v_mfma_f32_16x16x32_bf16 v[6:9], v[150:153], v[220:223], v[6:9]
	v_mfma_f32_16x16x32_bf16 v[22:25], v[150:153], v[182:185], v[22:25]
	v_mfma_f32_16x16x32_bf16 v[22:25], v[146:149], v[178:181], v[22:25]
	v_mfma_f32_16x16x32_bf16 v[38:41], v[146:149], v[170:173], v[38:41]
	v_mfma_f32_16x16x32_bf16 v[38:41], v[150:153], v[174:177], v[38:41]
	v_mfma_f32_16x16x32_bf16 v[54:57], v[150:153], v[166:169], v[54:57]
	v_mfma_f32_16x16x32_bf16 v[54:57], v[146:149], v[162:165], v[54:57]
	s_setprio 0
	s_barrier
	s_add_i32 s70, s70, 2
	s_add_u32 s61, s61, 0x100
	s_addc_u32 s69, s69, 0
	s_cmpk_gt_u32 s70, 0xa9
	s_mov_b64 s[44:45], s[46:47]
	s_cbranch_scc0 .LBB0_983
	s_and_b64 vcc, exec, s[30:31]
	s_cbranch_vccz .LBB0_986
	s_barrier
